# gate tensor re-laid out fragment-major (each P4 wave-load of gates is 512 contiguous bytes); P1 gate epilogue stores 8-byte pieces into that order, P4 mid hook and end epilogue rewritten for it; plus
# speedup vs baseline: 1.0093x; 1.0043x over previous
.LBB0_138:
	s_cmp_gt_u32 s94, 7
	s_cbranch_scc0 .LBB0_140
	v_ashrrev_i32_e32 v141, 31, v140
	s_lshl_b32 s54, s12, 19
	s_lshl_b32 s12, s94, 8
	s_addk_i32 s12, 0xf800
	v_lshl_add_u64 v[142:143], s[12:13], 2, v[134:135]
	global_load_dwordx4 v[186:189], v[142:143], off
	global_load_dwordx4 v[190:193], v[142:143], off offset:16
	global_load_dwordx4 v[194:197], v[142:143], off offset:32
	global_load_dwordx4 v[198:201], v[142:143], off offset:48
	v_lshlrev_b32_e32 v185, 2, v140
	global_load_dword v202, v185, s[18:19]
	global_load_dword v203, v185, s[18:19] offset:64
	global_load_dword v204, v185, s[18:19] offset:128
	global_load_dword v205, v185, s[18:19] offset:192
	global_load_dword v206, v185, s[18:19] offset:512
	global_load_dword v207, v185, s[18:19] offset:576
	global_load_dword v208, v185, s[18:19] offset:640
	global_load_dword v209, v185, s[18:19] offset:704
	s_sub_i32 s55, s94, 8
	s_lshl_b32 s55, s55, 16
	s_add_i32 s54, s54, s55
	v_and_b32_e32 v146, 15, v165
	v_lshlrev_b32_e32 v146, 3, v146
	v_and_b32_e32 v147, 16, v165
	v_lshl_or_b32 v146, v147, 4, v146
	v_and_b32_e32 v147, 0x60, v165
	v_lshl_or_b32 v146, v147, 8, v146
	v_and_b32_e32 v147, 0x80, v165
	v_lshl_or_b32 v146, v147, 2, v146
	v_and_b32_e32 v147, 0x100, v165
	v_lshl_or_b32 v146, v147, 7, v146
	v_and_b32_e32 v147, 0xf0, v165
	v_sub_u32_e32 v146, v146, v147
	v_add_u32_e32 v146, s54, v146
	v_mov_b32_e32 v147, 0
	v_lshl_add_u64 v[148:149], v[132:133], 0, v[146:147]
	v_mov_b32_e32 v146, 0x1000
	v_lshl_add_u64 v[146:147], v[148:149], 0, v[146:147]
	s_mov_b64 s[54:55], 0
	s_waitcnt vmcnt(8)
	v_mul_f32_e32 v186, 0xbfb8aa3b, v186
	v_mul_f32_e32 v187, 0xbfb8aa3b, v187
	v_mul_f32_e32 v188, 0xbfb8aa3b, v188
	v_mul_f32_e32 v189, 0xbfb8aa3b, v189
	v_mul_f32_e32 v190, 0xbfb8aa3b, v190
	v_mul_f32_e32 v191, 0xbfb8aa3b, v191
	v_mul_f32_e32 v192, 0xbfb8aa3b, v192
	v_mul_f32_e32 v193, 0xbfb8aa3b, v193
	v_mul_f32_e32 v194, 0xbfb8aa3b, v194
	v_mul_f32_e32 v195, 0xbfb8aa3b, v195
	v_mul_f32_e32 v196, 0xbfb8aa3b, v196
	v_mul_f32_e32 v197, 0xbfb8aa3b, v197
	v_mul_f32_e32 v198, 0xbfb8aa3b, v198
	v_mul_f32_e32 v199, 0xbfb8aa3b, v199
	v_mul_f32_e32 v200, 0xbfb8aa3b, v200
	v_mul_f32_e32 v201, 0xbfb8aa3b, v201
	s_waitcnt vmcnt(7)
	v_mul_f32_e32 v130, 0xbfb8aa3b, v202
	v_fma_f32 v210, v124, v130, v186
	v_fma_f32 v211, v125, v130, v187
	v_fma_f32 v212, v126, v130, v188
	v_fma_f32 v213, v127, v130, v189
	v_fma_f32 v214, v120, v130, v190
	v_fma_f32 v215, v121, v130, v191
	v_fma_f32 v216, v122, v130, v192
	v_fma_f32 v217, v123, v130, v193
	v_fma_f32 v218, v116, v130, v194
	v_fma_f32 v219, v117, v130, v195
	v_fma_f32 v220, v118, v130, v196
	v_fma_f32 v221, v119, v130, v197
	v_fma_f32 v222, v112, v130, v198
	v_fma_f32 v223, v113, v130, v199
	v_fma_f32 v224, v114, v130, v200
	v_fma_f32 v225, v115, v130, v201
	v_exp_f32_e32 v210, v210
	v_exp_f32_e32 v211, v211
	v_exp_f32_e32 v212, v212
	v_exp_f32_e32 v213, v213
	v_exp_f32_e32 v214, v214
	v_exp_f32_e32 v215, v215
	v_exp_f32_e32 v216, v216
	v_exp_f32_e32 v217, v217
	v_exp_f32_e32 v218, v218
	v_exp_f32_e32 v219, v219
	v_exp_f32_e32 v220, v220
	v_exp_f32_e32 v221, v221
	v_exp_f32_e32 v222, v222
	v_exp_f32_e32 v223, v223
	v_exp_f32_e32 v224, v224
	v_exp_f32_e32 v225, v225
	v_add_f32_e32 v210, 1.0, v210
	v_add_f32_e32 v211, 1.0, v211
	v_add_f32_e32 v212, 1.0, v212
	v_add_f32_e32 v213, 1.0, v213
	v_add_f32_e32 v214, 1.0, v214
	v_add_f32_e32 v215, 1.0, v215
	v_add_f32_e32 v216, 1.0, v216
	v_add_f32_e32 v217, 1.0, v217
	v_add_f32_e32 v218, 1.0, v218
	v_add_f32_e32 v219, 1.0, v219
	v_add_f32_e32 v220, 1.0, v220
	v_add_f32_e32 v221, 1.0, v221
	v_add_f32_e32 v222, 1.0, v222
	v_add_f32_e32 v223, 1.0, v223
	v_add_f32_e32 v224, 1.0, v224
	v_add_f32_e32 v225, 1.0, v225
	v_rcp_f32_e32 v210, v210
	v_rcp_f32_e32 v211, v211
	v_rcp_f32_e32 v212, v212
	v_rcp_f32_e32 v213, v213
	v_rcp_f32_e32 v214, v214
	v_rcp_f32_e32 v215, v215
	v_rcp_f32_e32 v216, v216
	v_rcp_f32_e32 v217, v217
	v_rcp_f32_e32 v218, v218
	v_rcp_f32_e32 v219, v219
	v_rcp_f32_e32 v220, v220
	v_rcp_f32_e32 v221, v221
	v_rcp_f32_e32 v222, v222
	v_rcp_f32_e32 v223, v223
	v_rcp_f32_e32 v224, v224
	v_rcp_f32_e32 v225, v225
	v_fma_f32 v210, v210, s84, 0.5
	v_fma_f32 v211, v211, s84, 0.5
	v_fma_f32 v212, v212, s84, 0.5
	v_fma_f32 v213, v213, s84, 0.5
	v_fma_f32 v214, v214, s84, 0.5
	v_fma_f32 v215, v215, s84, 0.5
	v_fma_f32 v216, v216, s84, 0.5
	v_fma_f32 v217, v217, s84, 0.5
	v_fma_f32 v218, v218, s84, 0.5
	v_fma_f32 v219, v219, s84, 0.5
	v_fma_f32 v220, v220, s84, 0.5
	v_fma_f32 v221, v221, s84, 0.5
	v_fma_f32 v222, v222, s84, 0.5
	v_fma_f32 v223, v223, s84, 0.5
	v_fma_f32 v224, v224, s84, 0.5
	v_fma_f32 v225, v225, s84, 0.5
	v_med3_f32 v210, v210, 1.0, v182
	v_med3_f32 v211, v211, 1.0, v182
	v_med3_f32 v212, v212, 1.0, v182
	v_med3_f32 v213, v213, 1.0, v182
	v_med3_f32 v214, v214, 1.0, v182
	v_med3_f32 v215, v215, 1.0, v182
	v_med3_f32 v216, v216, 1.0, v182
	v_med3_f32 v217, v217, 1.0, v182
	v_med3_f32 v218, v218, 1.0, v182
	v_med3_f32 v219, v219, 1.0, v182
	v_med3_f32 v220, v220, 1.0, v182
	v_med3_f32 v221, v221, 1.0, v182
	v_med3_f32 v222, v222, 1.0, v182
	v_med3_f32 v223, v223, 1.0, v182
	v_med3_f32 v224, v224, 1.0, v182
	v_med3_f32 v225, v225, 1.0, v182
	v_cvt_u32_f32_e32 v210, v210
	v_cvt_u32_f32_e32 v211, v211
	v_cvt_u32_f32_sdwa v212, v212 dst_sel:WORD_1 dst_unused:UNUSED_PAD src0_sel:DWORD
	v_cvt_u32_f32_sdwa v213, v213 dst_sel:BYTE_3 dst_unused:UNUSED_PAD src0_sel:DWORD
	v_cvt_u32_f32_e32 v214, v214
	v_cvt_u32_f32_e32 v215, v215
	v_cvt_u32_f32_sdwa v216, v216 dst_sel:WORD_1 dst_unused:UNUSED_PAD src0_sel:DWORD
	v_cvt_u32_f32_sdwa v217, v217 dst_sel:BYTE_3 dst_unused:UNUSED_PAD src0_sel:DWORD
	v_cvt_u32_f32_e32 v218, v218
	v_cvt_u32_f32_e32 v219, v219
	v_cvt_u32_f32_sdwa v220, v220 dst_sel:WORD_1 dst_unused:UNUSED_PAD src0_sel:DWORD
	v_cvt_u32_f32_sdwa v221, v221 dst_sel:BYTE_3 dst_unused:UNUSED_PAD src0_sel:DWORD
	v_cvt_u32_f32_e32 v222, v222
	v_cvt_u32_f32_e32 v223, v223
	v_cvt_u32_f32_sdwa v224, v224 dst_sel:WORD_1 dst_unused:UNUSED_PAD src0_sel:DWORD
	v_cvt_u32_f32_sdwa v225, v225 dst_sel:BYTE_3 dst_unused:UNUSED_PAD src0_sel:DWORD
	v_lshl_or_b32 v210, v211, 8, v210
	v_lshl_or_b32 v214, v215, 8, v214
	v_lshl_or_b32 v218, v219, 8, v218
	v_lshl_or_b32 v222, v223, 8, v222
	v_or3_b32 v236, v210, v212, v213
	v_or3_b32 v237, v214, v216, v217
	v_or3_b32 v238, v218, v220, v221
	v_or3_b32 v239, v222, v224, v225
	global_store_dwordx2 v[148:149], v[236:237], off nt
	global_store_dwordx2 v[148:149], v[238:239], off offset:128 nt
	s_waitcnt vmcnt(8)
	v_mul_f32_e32 v130, 0xbfb8aa3b, v203
	v_fma_f32 v210, v108, v130, v186
	v_fma_f32 v211, v109, v130, v187
	v_fma_f32 v212, v110, v130, v188
	v_fma_f32 v213, v111, v130, v189
	v_fma_f32 v214, v104, v130, v190
	v_fma_f32 v215, v105, v130, v191
	v_fma_f32 v216, v106, v130, v192
	v_fma_f32 v217, v107, v130, v193
	v_fma_f32 v218, v100, v130, v194
	v_fma_f32 v219, v101, v130, v195
	v_fma_f32 v220, v102, v130, v196
	v_fma_f32 v221, v103, v130, v197
	v_fma_f32 v222, v96, v130, v198
	v_fma_f32 v223, v97, v130, v199
	v_fma_f32 v224, v98, v130, v200
	v_fma_f32 v225, v99, v130, v201
	v_exp_f32_e32 v210, v210
	v_exp_f32_e32 v211, v211
	v_exp_f32_e32 v212, v212
	v_exp_f32_e32 v213, v213
	v_exp_f32_e32 v214, v214
	v_exp_f32_e32 v215, v215
	v_exp_f32_e32 v216, v216
	v_exp_f32_e32 v217, v217
	v_exp_f32_e32 v218, v218
	v_exp_f32_e32 v219, v219
	v_exp_f32_e32 v220, v220
	v_exp_f32_e32 v221, v221
	v_exp_f32_e32 v222, v222
	v_exp_f32_e32 v223, v223
	v_exp_f32_e32 v224, v224
	v_exp_f32_e32 v225, v225
	v_add_f32_e32 v210, 1.0, v210
	v_add_f32_e32 v211, 1.0, v211
	v_add_f32_e32 v212, 1.0, v212
	v_add_f32_e32 v213, 1.0, v213
	v_add_f32_e32 v214, 1.0, v214
	v_add_f32_e32 v215, 1.0, v215
	v_add_f32_e32 v216, 1.0, v216
	v_add_f32_e32 v217, 1.0, v217
	v_add_f32_e32 v218, 1.0, v218
	v_add_f32_e32 v219, 1.0, v219
	v_add_f32_e32 v220, 1.0, v220
	v_add_f32_e32 v221, 1.0, v221
	v_add_f32_e32 v222, 1.0, v222
	v_add_f32_e32 v223, 1.0, v223
	v_add_f32_e32 v224, 1.0, v224
	v_add_f32_e32 v225, 1.0, v225
	v_rcp_f32_e32 v210, v210
	v_rcp_f32_e32 v211, v211
	v_rcp_f32_e32 v212, v212
	v_rcp_f32_e32 v213, v213
	v_rcp_f32_e32 v214, v214
	v_rcp_f32_e32 v215, v215
	v_rcp_f32_e32 v216, v216
	v_rcp_f32_e32 v217, v217
	v_rcp_f32_e32 v218, v218
	v_rcp_f32_e32 v219, v219
	v_rcp_f32_e32 v220, v220
	v_rcp_f32_e32 v221, v221
	v_rcp_f32_e32 v222, v222
	v_rcp_f32_e32 v223, v223
	v_rcp_f32_e32 v224, v224
	v_rcp_f32_e32 v225, v225
	v_fma_f32 v210, v210, s84, 0.5
	v_fma_f32 v211, v211, s84, 0.5
	v_fma_f32 v212, v212, s84, 0.5
	v_fma_f32 v213, v213, s84, 0.5
	v_fma_f32 v214, v214, s84, 0.5
	v_fma_f32 v215, v215, s84, 0.5
	v_fma_f32 v216, v216, s84, 0.5
	v_fma_f32 v217, v217, s84, 0.5
	v_fma_f32 v218, v218, s84, 0.5
	v_fma_f32 v219, v219, s84, 0.5
	v_fma_f32 v220, v220, s84, 0.5
	v_fma_f32 v221, v221, s84, 0.5
	v_fma_f32 v222, v222, s84, 0.5
	v_fma_f32 v223, v223, s84, 0.5
	v_fma_f32 v224, v224, s84, 0.5
	v_fma_f32 v225, v225, s84, 0.5
	v_med3_f32 v210, v210, 1.0, v182
	v_med3_f32 v211, v211, 1.0, v182
	v_med3_f32 v212, v212, 1.0, v182
	v_med3_f32 v213, v213, 1.0, v182
	v_med3_f32 v214, v214, 1.0, v182
	v_med3_f32 v215, v215, 1.0, v182
	v_med3_f32 v216, v216, 1.0, v182
	v_med3_f32 v217, v217, 1.0, v182
	v_med3_f32 v218, v218, 1.0, v182
	v_med3_f32 v219, v219, 1.0, v182
	v_med3_f32 v220, v220, 1.0, v182
	v_med3_f32 v221, v221, 1.0, v182
	v_med3_f32 v222, v222, 1.0, v182
	v_med3_f32 v223, v223, 1.0, v182
	v_med3_f32 v224, v224, 1.0, v182
	v_med3_f32 v225, v225, 1.0, v182
	v_cvt_u32_f32_e32 v210, v210
	v_cvt_u32_f32_e32 v211, v211
	v_cvt_u32_f32_sdwa v212, v212 dst_sel:WORD_1 dst_unused:UNUSED_PAD src0_sel:DWORD
	v_cvt_u32_f32_sdwa v213, v213 dst_sel:BYTE_3 dst_unused:UNUSED_PAD src0_sel:DWORD
	v_cvt_u32_f32_e32 v214, v214
	v_cvt_u32_f32_e32 v215, v215
	v_cvt_u32_f32_sdwa v216, v216 dst_sel:WORD_1 dst_unused:UNUSED_PAD src0_sel:DWORD
	v_cvt_u32_f32_sdwa v217, v217 dst_sel:BYTE_3 dst_unused:UNUSED_PAD src0_sel:DWORD
	v_cvt_u32_f32_e32 v218, v218
	v_cvt_u32_f32_e32 v219, v219
	v_cvt_u32_f32_sdwa v220, v220 dst_sel:WORD_1 dst_unused:UNUSED_PAD src0_sel:DWORD
	v_cvt_u32_f32_sdwa v221, v221 dst_sel:BYTE_3 dst_unused:UNUSED_PAD src0_sel:DWORD
	v_cvt_u32_f32_e32 v222, v222
	v_cvt_u32_f32_e32 v223, v223
	v_cvt_u32_f32_sdwa v224, v224 dst_sel:WORD_1 dst_unused:UNUSED_PAD src0_sel:DWORD
	v_cvt_u32_f32_sdwa v225, v225 dst_sel:BYTE_3 dst_unused:UNUSED_PAD src0_sel:DWORD
	v_lshl_or_b32 v210, v211, 8, v210
	v_lshl_or_b32 v214, v215, 8, v214
	v_lshl_or_b32 v218, v219, 8, v218
	v_lshl_or_b32 v222, v223, 8, v222
	v_or3_b32 v236, v210, v212, v213
	v_or3_b32 v237, v214, v216, v217
	v_or3_b32 v238, v218, v220, v221
	v_or3_b32 v239, v222, v224, v225
	global_store_dwordx2 v[148:149], v[236:237], off offset:1024 nt
	global_store_dwordx2 v[148:149], v[238:239], off offset:1152 nt
	s_waitcnt vmcnt(9)
	v_mul_f32_e32 v130, 0xbfb8aa3b, v204
	v_fma_f32 v210, v92, v130, v186
	v_fma_f32 v211, v93, v130, v187
	v_fma_f32 v212, v94, v130, v188
	v_fma_f32 v213, v95, v130, v189
	v_fma_f32 v214, v88, v130, v190
	v_fma_f32 v215, v89, v130, v191
	v_fma_f32 v216, v90, v130, v192
	v_fma_f32 v217, v91, v130, v193
	v_fma_f32 v218, v84, v130, v194
	v_fma_f32 v219, v85, v130, v195
	v_fma_f32 v220, v86, v130, v196
	v_fma_f32 v221, v87, v130, v197
	v_fma_f32 v222, v80, v130, v198
	v_fma_f32 v223, v81, v130, v199
	v_fma_f32 v224, v82, v130, v200
	v_fma_f32 v225, v83, v130, v201
	v_exp_f32_e32 v210, v210
	v_exp_f32_e32 v211, v211
	v_exp_f32_e32 v212, v212
	v_exp_f32_e32 v213, v213
	v_exp_f32_e32 v214, v214
	v_exp_f32_e32 v215, v215
	v_exp_f32_e32 v216, v216
	v_exp_f32_e32 v217, v217
	v_exp_f32_e32 v218, v218
	v_exp_f32_e32 v219, v219
	v_exp_f32_e32 v220, v220
	v_exp_f32_e32 v221, v221
	v_exp_f32_e32 v222, v222
	v_exp_f32_e32 v223, v223
	v_exp_f32_e32 v224, v224
	v_exp_f32_e32 v225, v225
	v_add_f32_e32 v210, 1.0, v210
	v_add_f32_e32 v211, 1.0, v211
	v_add_f32_e32 v212, 1.0, v212
	v_add_f32_e32 v213, 1.0, v213
	v_add_f32_e32 v214, 1.0, v214
	v_add_f32_e32 v215, 1.0, v215
	v_add_f32_e32 v216, 1.0, v216
	v_add_f32_e32 v217, 1.0, v217
	v_add_f32_e32 v218, 1.0, v218
	v_add_f32_e32 v219, 1.0, v219
	v_add_f32_e32 v220, 1.0, v220
	v_add_f32_e32 v221, 1.0, v221
	v_add_f32_e32 v222, 1.0, v222
	v_add_f32_e32 v223, 1.0, v223
	v_add_f32_e32 v224, 1.0, v224
	v_add_f32_e32 v225, 1.0, v225
	v_rcp_f32_e32 v210, v210
	v_rcp_f32_e32 v211, v211
	v_rcp_f32_e32 v212, v212
	v_rcp_f32_e32 v213, v213
	v_rcp_f32_e32 v214, v214
	v_rcp_f32_e32 v215, v215
	v_rcp_f32_e32 v216, v216
	v_rcp_f32_e32 v217, v217
	v_rcp_f32_e32 v218, v218
	v_rcp_f32_e32 v219, v219
	v_rcp_f32_e32 v220, v220
	v_rcp_f32_e32 v221, v221
	v_rcp_f32_e32 v222, v222
	v_rcp_f32_e32 v223, v223
	v_rcp_f32_e32 v224, v224
	v_rcp_f32_e32 v225, v225
	v_fma_f32 v210, v210, s84, 0.5
	v_fma_f32 v211, v211, s84, 0.5
	v_fma_f32 v212, v212, s84, 0.5
	v_fma_f32 v213, v213, s84, 0.5
	v_fma_f32 v214, v214, s84, 0.5
	v_fma_f32 v215, v215, s84, 0.5
	v_fma_f32 v216, v216, s84, 0.5
	v_fma_f32 v217, v217, s84, 0.5
	v_fma_f32 v218, v218, s84, 0.5
	v_fma_f32 v219, v219, s84, 0.5
	v_fma_f32 v220, v220, s84, 0.5
	v_fma_f32 v221, v221, s84, 0.5
	v_fma_f32 v222, v222, s84, 0.5
	v_fma_f32 v223, v223, s84, 0.5
	v_fma_f32 v224, v224, s84, 0.5
	v_fma_f32 v225, v225, s84, 0.5
	v_med3_f32 v210, v210, 1.0, v182
	v_med3_f32 v211, v211, 1.0, v182
	v_med3_f32 v212, v212, 1.0, v182
	v_med3_f32 v213, v213, 1.0, v182
	v_med3_f32 v214, v214, 1.0, v182
	v_med3_f32 v215, v215, 1.0, v182
	v_med3_f32 v216, v216, 1.0, v182
	v_med3_f32 v217, v217, 1.0, v182
	v_med3_f32 v218, v218, 1.0, v182
	v_med3_f32 v219, v219, 1.0, v182
	v_med3_f32 v220, v220, 1.0, v182
	v_med3_f32 v221, v221, 1.0, v182
	v_med3_f32 v222, v222, 1.0, v182
	v_med3_f32 v223, v223, 1.0, v182
	v_med3_f32 v224, v224, 1.0, v182
	v_med3_f32 v225, v225, 1.0, v182
	v_cvt_u32_f32_e32 v210, v210
	v_cvt_u32_f32_e32 v211, v211
	v_cvt_u32_f32_sdwa v212, v212 dst_sel:WORD_1 dst_unused:UNUSED_PAD src0_sel:DWORD
	v_cvt_u32_f32_sdwa v213, v213 dst_sel:BYTE_3 dst_unused:UNUSED_PAD src0_sel:DWORD
	v_cvt_u32_f32_e32 v214, v214
	v_cvt_u32_f32_e32 v215, v215
	v_cvt_u32_f32_sdwa v216, v216 dst_sel:WORD_1 dst_unused:UNUSED_PAD src0_sel:DWORD
	v_cvt_u32_f32_sdwa v217, v217 dst_sel:BYTE_3 dst_unused:UNUSED_PAD src0_sel:DWORD
	v_cvt_u32_f32_e32 v218, v218
	v_cvt_u32_f32_e32 v219, v219
	v_cvt_u32_f32_sdwa v220, v220 dst_sel:WORD_1 dst_unused:UNUSED_PAD src0_sel:DWORD
	v_cvt_u32_f32_sdwa v221, v221 dst_sel:BYTE_3 dst_unused:UNUSED_PAD src0_sel:DWORD
	v_cvt_u32_f32_e32 v222, v222
	v_cvt_u32_f32_e32 v223, v223
	v_cvt_u32_f32_sdwa v224, v224 dst_sel:WORD_1 dst_unused:UNUSED_PAD src0_sel:DWORD
	v_cvt_u32_f32_sdwa v225, v225 dst_sel:BYTE_3 dst_unused:UNUSED_PAD src0_sel:DWORD
	v_lshl_or_b32 v210, v211, 8, v210
	v_lshl_or_b32 v214, v215, 8, v214
	v_lshl_or_b32 v218, v219, 8, v218
	v_lshl_or_b32 v222, v223, 8, v222
	v_or3_b32 v236, v210, v212, v213
	v_or3_b32 v237, v214, v216, v217
	v_or3_b32 v238, v218, v220, v221
	v_or3_b32 v239, v222, v224, v225
	global_store_dwordx2 v[148:149], v[236:237], off offset:2048 nt
	global_store_dwordx2 v[148:149], v[238:239], off offset:2176 nt
	s_waitcnt vmcnt(10)
	v_mul_f32_e32 v130, 0xbfb8aa3b, v205
	v_fma_f32 v210, v76, v130, v186
	v_fma_f32 v211, v77, v130, v187
	v_fma_f32 v212, v78, v130, v188
	v_fma_f32 v213, v79, v130, v189
	v_fma_f32 v214, v72, v130, v190
	v_fma_f32 v215, v73, v130, v191
	v_fma_f32 v216, v74, v130, v192
	v_fma_f32 v217, v75, v130, v193
	v_fma_f32 v218, v68, v130, v194
	v_fma_f32 v219, v69, v130, v195
	v_fma_f32 v220, v70, v130, v196
	v_fma_f32 v221, v71, v130, v197
	v_fma_f32 v222, v64, v130, v198
	v_fma_f32 v223, v65, v130, v199
	v_fma_f32 v224, v66, v130, v200
	v_fma_f32 v225, v67, v130, v201
	v_exp_f32_e32 v210, v210
	v_exp_f32_e32 v211, v211
	v_exp_f32_e32 v212, v212
	v_exp_f32_e32 v213, v213
	v_exp_f32_e32 v214, v214
	v_exp_f32_e32 v215, v215
	v_exp_f32_e32 v216, v216
	v_exp_f32_e32 v217, v217
	v_exp_f32_e32 v218, v218
	v_exp_f32_e32 v219, v219
	v_exp_f32_e32 v220, v220
	v_exp_f32_e32 v221, v221
	v_exp_f32_e32 v222, v222
	v_exp_f32_e32 v223, v223
	v_exp_f32_e32 v224, v224
	v_exp_f32_e32 v225, v225
	v_add_f32_e32 v210, 1.0, v210
	v_add_f32_e32 v211, 1.0, v211
	v_add_f32_e32 v212, 1.0, v212
	v_add_f32_e32 v213, 1.0, v213
	v_add_f32_e32 v214, 1.0, v214
	v_add_f32_e32 v215, 1.0, v215
	v_add_f32_e32 v216, 1.0, v216
	v_add_f32_e32 v217, 1.0, v217
	v_add_f32_e32 v218, 1.0, v218
	v_add_f32_e32 v219, 1.0, v219
	v_add_f32_e32 v220, 1.0, v220
	v_add_f32_e32 v221, 1.0, v221
	v_add_f32_e32 v222, 1.0, v222
	v_add_f32_e32 v223, 1.0, v223
	v_add_f32_e32 v224, 1.0, v224
	v_add_f32_e32 v225, 1.0, v225
	v_rcp_f32_e32 v210, v210
	v_rcp_f32_e32 v211, v211
	v_rcp_f32_e32 v212, v212
	v_rcp_f32_e32 v213, v213
	v_rcp_f32_e32 v214, v214
	v_rcp_f32_e32 v215, v215
	v_rcp_f32_e32 v216, v216
	v_rcp_f32_e32 v217, v217
	v_rcp_f32_e32 v218, v218
	v_rcp_f32_e32 v219, v219
	v_rcp_f32_e32 v220, v220
	v_rcp_f32_e32 v221, v221
	v_rcp_f32_e32 v222, v222
	v_rcp_f32_e32 v223, v223
	v_rcp_f32_e32 v224, v224
	v_rcp_f32_e32 v225, v225
	v_fma_f32 v210, v210, s84, 0.5
	v_fma_f32 v211, v211, s84, 0.5
	v_fma_f32 v212, v212, s84, 0.5
	v_fma_f32 v213, v213, s84, 0.5
	v_fma_f32 v214, v214, s84, 0.5
	v_fma_f32 v215, v215, s84, 0.5
	v_fma_f32 v216, v216, s84, 0.5
	v_fma_f32 v217, v217, s84, 0.5
	v_fma_f32 v218, v218, s84, 0.5
	v_fma_f32 v219, v219, s84, 0.5
	v_fma_f32 v220, v220, s84, 0.5
	v_fma_f32 v221, v221, s84, 0.5
	v_fma_f32 v222, v222, s84, 0.5
	v_fma_f32 v223, v223, s84, 0.5
	v_fma_f32 v224, v224, s84, 0.5
	v_fma_f32 v225, v225, s84, 0.5
	v_med3_f32 v210, v210, 1.0, v182
	v_med3_f32 v211, v211, 1.0, v182
	v_med3_f32 v212, v212, 1.0, v182
	v_med3_f32 v213, v213, 1.0, v182
	v_med3_f32 v214, v214, 1.0, v182
	v_med3_f32 v215, v215, 1.0, v182
	v_med3_f32 v216, v216, 1.0, v182
	v_med3_f32 v217, v217, 1.0, v182
	v_med3_f32 v218, v218, 1.0, v182
	v_med3_f32 v219, v219, 1.0, v182
	v_med3_f32 v220, v220, 1.0, v182
	v_med3_f32 v221, v221, 1.0, v182
	v_med3_f32 v222, v222, 1.0, v182
	v_med3_f32 v223, v223, 1.0, v182
	v_med3_f32 v224, v224, 1.0, v182
	v_med3_f32 v225, v225, 1.0, v182
	v_cvt_u32_f32_e32 v210, v210
	v_cvt_u32_f32_e32 v211, v211
	v_cvt_u32_f32_sdwa v212, v212 dst_sel:WORD_1 dst_unused:UNUSED_PAD src0_sel:DWORD
	v_cvt_u32_f32_sdwa v213, v213 dst_sel:BYTE_3 dst_unused:UNUSED_PAD src0_sel:DWORD
	v_cvt_u32_f32_e32 v214, v214
	v_cvt_u32_f32_e32 v215, v215
	v_cvt_u32_f32_sdwa v216, v216 dst_sel:WORD_1 dst_unused:UNUSED_PAD src0_sel:DWORD
	v_cvt_u32_f32_sdwa v217, v217 dst_sel:BYTE_3 dst_unused:UNUSED_PAD src0_sel:DWORD
	v_cvt_u32_f32_e32 v218, v218
	v_cvt_u32_f32_e32 v219, v219
	v_cvt_u32_f32_sdwa v220, v220 dst_sel:WORD_1 dst_unused:UNUSED_PAD src0_sel:DWORD
	v_cvt_u32_f32_sdwa v221, v221 dst_sel:BYTE_3 dst_unused:UNUSED_PAD src0_sel:DWORD
	v_cvt_u32_f32_e32 v222, v222
	v_cvt_u32_f32_e32 v223, v223
	v_cvt_u32_f32_sdwa v224, v224 dst_sel:WORD_1 dst_unused:UNUSED_PAD src0_sel:DWORD
	v_cvt_u32_f32_sdwa v225, v225 dst_sel:BYTE_3 dst_unused:UNUSED_PAD src0_sel:DWORD
	v_lshl_or_b32 v210, v211, 8, v210
	v_lshl_or_b32 v214, v215, 8, v214
	v_lshl_or_b32 v218, v219, 8, v218
	v_lshl_or_b32 v222, v223, 8, v222
	v_or3_b32 v236, v210, v212, v213
	v_or3_b32 v237, v214, v216, v217
	v_or3_b32 v238, v218, v220, v221
	v_or3_b32 v239, v222, v224, v225
	global_store_dwordx2 v[148:149], v[236:237], off offset:3072 nt
	global_store_dwordx2 v[148:149], v[238:239], off offset:3200 nt
	s_waitcnt vmcnt(11)
	v_mul_f32_e32 v130, 0xbfb8aa3b, v206
	v_fma_f32 v210, v60, v130, v186
	v_fma_f32 v211, v61, v130, v187
	v_fma_f32 v212, v62, v130, v188
	v_fma_f32 v213, v63, v130, v189
	v_fma_f32 v214, v56, v130, v190
	v_fma_f32 v215, v57, v130, v191
	v_fma_f32 v216, v58, v130, v192
	v_fma_f32 v217, v59, v130, v193
	v_fma_f32 v218, v52, v130, v194
	v_fma_f32 v219, v53, v130, v195
	v_fma_f32 v220, v54, v130, v196
	v_fma_f32 v221, v55, v130, v197
	v_fma_f32 v222, v48, v130, v198
	v_fma_f32 v223, v49, v130, v199
	v_fma_f32 v224, v50, v130, v200
	v_fma_f32 v225, v51, v130, v201
	v_exp_f32_e32 v210, v210
	v_exp_f32_e32 v211, v211
	v_exp_f32_e32 v212, v212
	v_exp_f32_e32 v213, v213
	v_exp_f32_e32 v214, v214
	v_exp_f32_e32 v215, v215
	v_exp_f32_e32 v216, v216
	v_exp_f32_e32 v217, v217
	v_exp_f32_e32 v218, v218
	v_exp_f32_e32 v219, v219
	v_exp_f32_e32 v220, v220
	v_exp_f32_e32 v221, v221
	v_exp_f32_e32 v222, v222
	v_exp_f32_e32 v223, v223
	v_exp_f32_e32 v224, v224
	v_exp_f32_e32 v225, v225
	v_add_f32_e32 v210, 1.0, v210
	v_add_f32_e32 v211, 1.0, v211
	v_add_f32_e32 v212, 1.0, v212
	v_add_f32_e32 v213, 1.0, v213
	v_add_f32_e32 v214, 1.0, v214
	v_add_f32_e32 v215, 1.0, v215
	v_add_f32_e32 v216, 1.0, v216
	v_add_f32_e32 v217, 1.0, v217
	v_add_f32_e32 v218, 1.0, v218
	v_add_f32_e32 v219, 1.0, v219
	v_add_f32_e32 v220, 1.0, v220
	v_add_f32_e32 v221, 1.0, v221
	v_add_f32_e32 v222, 1.0, v222
	v_add_f32_e32 v223, 1.0, v223
	v_add_f32_e32 v224, 1.0, v224
	v_add_f32_e32 v225, 1.0, v225
	v_rcp_f32_e32 v210, v210
	v_rcp_f32_e32 v211, v211
	v_rcp_f32_e32 v212, v212
	v_rcp_f32_e32 v213, v213
	v_rcp_f32_e32 v214, v214
	v_rcp_f32_e32 v215, v215
	v_rcp_f32_e32 v216, v216
	v_rcp_f32_e32 v217, v217
	v_rcp_f32_e32 v218, v218
	v_rcp_f32_e32 v219, v219
	v_rcp_f32_e32 v220, v220
	v_rcp_f32_e32 v221, v221
	v_rcp_f32_e32 v222, v222
	v_rcp_f32_e32 v223, v223
	v_rcp_f32_e32 v224, v224
	v_rcp_f32_e32 v225, v225
	v_fma_f32 v210, v210, s84, 0.5
	v_fma_f32 v211, v211, s84, 0.5
	v_fma_f32 v212, v212, s84, 0.5
	v_fma_f32 v213, v213, s84, 0.5
	v_fma_f32 v214, v214, s84, 0.5
	v_fma_f32 v215, v215, s84, 0.5
	v_fma_f32 v216, v216, s84, 0.5
	v_fma_f32 v217, v217, s84, 0.5
	v_fma_f32 v218, v218, s84, 0.5
	v_fma_f32 v219, v219, s84, 0.5
	v_fma_f32 v220, v220, s84, 0.5
	v_fma_f32 v221, v221, s84, 0.5
	v_fma_f32 v222, v222, s84, 0.5
	v_fma_f32 v223, v223, s84, 0.5
	v_fma_f32 v224, v224, s84, 0.5
	v_fma_f32 v225, v225, s84, 0.5
	v_med3_f32 v210, v210, 1.0, v182
	v_med3_f32 v211, v211, 1.0, v182
	v_med3_f32 v212, v212, 1.0, v182
	v_med3_f32 v213, v213, 1.0, v182
	v_med3_f32 v214, v214, 1.0, v182
	v_med3_f32 v215, v215, 1.0, v182
	v_med3_f32 v216, v216, 1.0, v182
	v_med3_f32 v217, v217, 1.0, v182
	v_med3_f32 v218, v218, 1.0, v182
	v_med3_f32 v219, v219, 1.0, v182
	v_med3_f32 v220, v220, 1.0, v182
	v_med3_f32 v221, v221, 1.0, v182
	v_med3_f32 v222, v222, 1.0, v182
	v_med3_f32 v223, v223, 1.0, v182
	v_med3_f32 v224, v224, 1.0, v182
	v_med3_f32 v225, v225, 1.0, v182
	v_cvt_u32_f32_e32 v210, v210
	v_cvt_u32_f32_e32 v211, v211
	v_cvt_u32_f32_sdwa v212, v212 dst_sel:WORD_1 dst_unused:UNUSED_PAD src0_sel:DWORD
	v_cvt_u32_f32_sdwa v213, v213 dst_sel:BYTE_3 dst_unused:UNUSED_PAD src0_sel:DWORD
	v_cvt_u32_f32_e32 v214, v214
	v_cvt_u32_f32_e32 v215, v215
	v_cvt_u32_f32_sdwa v216, v216 dst_sel:WORD_1 dst_unused:UNUSED_PAD src0_sel:DWORD
	v_cvt_u32_f32_sdwa v217, v217 dst_sel:BYTE_3 dst_unused:UNUSED_PAD src0_sel:DWORD
	v_cvt_u32_f32_e32 v218, v218
	v_cvt_u32_f32_e32 v219, v219
	v_cvt_u32_f32_sdwa v220, v220 dst_sel:WORD_1 dst_unused:UNUSED_PAD src0_sel:DWORD
	v_cvt_u32_f32_sdwa v221, v221 dst_sel:BYTE_3 dst_unused:UNUSED_PAD src0_sel:DWORD
	v_cvt_u32_f32_e32 v222, v222
	v_cvt_u32_f32_e32 v223, v223
	v_cvt_u32_f32_sdwa v224, v224 dst_sel:WORD_1 dst_unused:UNUSED_PAD src0_sel:DWORD
	v_cvt_u32_f32_sdwa v225, v225 dst_sel:BYTE_3 dst_unused:UNUSED_PAD src0_sel:DWORD
	v_lshl_or_b32 v210, v211, 8, v210
	v_lshl_or_b32 v214, v215, 8, v214
	v_lshl_or_b32 v218, v219, 8, v218
	v_lshl_or_b32 v222, v223, 8, v222
	v_or3_b32 v236, v210, v212, v213
	v_or3_b32 v237, v214, v216, v217
	v_or3_b32 v238, v218, v220, v221
	v_or3_b32 v239, v222, v224, v225
	global_store_dwordx2 v[146:147], v[236:237], off nt
	global_store_dwordx2 v[146:147], v[238:239], off offset:128 nt
	s_waitcnt vmcnt(12)
	v_mul_f32_e32 v130, 0xbfb8aa3b, v207
	v_fma_f32 v210, v44, v130, v186
	v_fma_f32 v211, v45, v130, v187
	v_fma_f32 v212, v46, v130, v188
	v_fma_f32 v213, v47, v130, v189
	v_fma_f32 v214, v40, v130, v190
	v_fma_f32 v215, v41, v130, v191
	v_fma_f32 v216, v42, v130, v192
	v_fma_f32 v217, v43, v130, v193
	v_fma_f32 v218, v36, v130, v194
	v_fma_f32 v219, v37, v130, v195
	v_fma_f32 v220, v38, v130, v196
	v_fma_f32 v221, v39, v130, v197
	v_fma_f32 v222, v32, v130, v198
	v_fma_f32 v223, v33, v130, v199
	v_fma_f32 v224, v34, v130, v200
	v_fma_f32 v225, v35, v130, v201
	v_exp_f32_e32 v210, v210
	v_exp_f32_e32 v211, v211
	v_exp_f32_e32 v212, v212
	v_exp_f32_e32 v213, v213
	v_exp_f32_e32 v214, v214
	v_exp_f32_e32 v215, v215
	v_exp_f32_e32 v216, v216
	v_exp_f32_e32 v217, v217
	v_exp_f32_e32 v218, v218
	v_exp_f32_e32 v219, v219
	v_exp_f32_e32 v220, v220
	v_exp_f32_e32 v221, v221
	v_exp_f32_e32 v222, v222
	v_exp_f32_e32 v223, v223
	v_exp_f32_e32 v224, v224
	v_exp_f32_e32 v225, v225
	v_add_f32_e32 v210, 1.0, v210
	v_add_f32_e32 v211, 1.0, v211
	v_add_f32_e32 v212, 1.0, v212
	v_add_f32_e32 v213, 1.0, v213
	v_add_f32_e32 v214, 1.0, v214
	v_add_f32_e32 v215, 1.0, v215
	v_add_f32_e32 v216, 1.0, v216
	v_add_f32_e32 v217, 1.0, v217
	v_add_f32_e32 v218, 1.0, v218
	v_add_f32_e32 v219, 1.0, v219
	v_add_f32_e32 v220, 1.0, v220
	v_add_f32_e32 v221, 1.0, v221
	v_add_f32_e32 v222, 1.0, v222
	v_add_f32_e32 v223, 1.0, v223
	v_add_f32_e32 v224, 1.0, v224
	v_add_f32_e32 v225, 1.0, v225
	v_rcp_f32_e32 v210, v210
	v_rcp_f32_e32 v211, v211
	v_rcp_f32_e32 v212, v212
	v_rcp_f32_e32 v213, v213
	v_rcp_f32_e32 v214, v214
	v_rcp_f32_e32 v215, v215
	v_rcp_f32_e32 v216, v216
	v_rcp_f32_e32 v217, v217
	v_rcp_f32_e32 v218, v218
	v_rcp_f32_e32 v219, v219
	v_rcp_f32_e32 v220, v220
	v_rcp_f32_e32 v221, v221
	v_rcp_f32_e32 v222, v222
	v_rcp_f32_e32 v223, v223
	v_rcp_f32_e32 v224, v224
	v_rcp_f32_e32 v225, v225
	v_fma_f32 v210, v210, s84, 0.5
	v_fma_f32 v211, v211, s84, 0.5
	v_fma_f32 v212, v212, s84, 0.5
	v_fma_f32 v213, v213, s84, 0.5
	v_fma_f32 v214, v214, s84, 0.5
	v_fma_f32 v215, v215, s84, 0.5
	v_fma_f32 v216, v216, s84, 0.5
	v_fma_f32 v217, v217, s84, 0.5
	v_fma_f32 v218, v218, s84, 0.5
	v_fma_f32 v219, v219, s84, 0.5
	v_fma_f32 v220, v220, s84, 0.5
	v_fma_f32 v221, v221, s84, 0.5
	v_fma_f32 v222, v222, s84, 0.5
	v_fma_f32 v223, v223, s84, 0.5
	v_fma_f32 v224, v224, s84, 0.5
	v_fma_f32 v225, v225, s84, 0.5
	v_med3_f32 v210, v210, 1.0, v182
	v_med3_f32 v211, v211, 1.0, v182
	v_med3_f32 v212, v212, 1.0, v182
	v_med3_f32 v213, v213, 1.0, v182
	v_med3_f32 v214, v214, 1.0, v182
	v_med3_f32 v215, v215, 1.0, v182
	v_med3_f32 v216, v216, 1.0, v182
	v_med3_f32 v217, v217, 1.0, v182
	v_med3_f32 v218, v218, 1.0, v182
	v_med3_f32 v219, v219, 1.0, v182
	v_med3_f32 v220, v220, 1.0, v182
	v_med3_f32 v221, v221, 1.0, v182
	v_med3_f32 v222, v222, 1.0, v182
	v_med3_f32 v223, v223, 1.0, v182
	v_med3_f32 v224, v224, 1.0, v182
	v_med3_f32 v225, v225, 1.0, v182
	v_cvt_u32_f32_e32 v210, v210
	v_cvt_u32_f32_e32 v211, v211
	v_cvt_u32_f32_sdwa v212, v212 dst_sel:WORD_1 dst_unused:UNUSED_PAD src0_sel:DWORD
	v_cvt_u32_f32_sdwa v213, v213 dst_sel:BYTE_3 dst_unused:UNUSED_PAD src0_sel:DWORD
	v_cvt_u32_f32_e32 v214, v214
	v_cvt_u32_f32_e32 v215, v215
	v_cvt_u32_f32_sdwa v216, v216 dst_sel:WORD_1 dst_unused:UNUSED_PAD src0_sel:DWORD
	v_cvt_u32_f32_sdwa v217, v217 dst_sel:BYTE_3 dst_unused:UNUSED_PAD src0_sel:DWORD
	v_cvt_u32_f32_e32 v218, v218
	v_cvt_u32_f32_e32 v219, v219
	v_cvt_u32_f32_sdwa v220, v220 dst_sel:WORD_1 dst_unused:UNUSED_PAD src0_sel:DWORD
	v_cvt_u32_f32_sdwa v221, v221 dst_sel:BYTE_3 dst_unused:UNUSED_PAD src0_sel:DWORD
	v_cvt_u32_f32_e32 v222, v222
	v_cvt_u32_f32_e32 v223, v223
	v_cvt_u32_f32_sdwa v224, v224 dst_sel:WORD_1 dst_unused:UNUSED_PAD src0_sel:DWORD
	v_cvt_u32_f32_sdwa v225, v225 dst_sel:BYTE_3 dst_unused:UNUSED_PAD src0_sel:DWORD
	v_lshl_or_b32 v210, v211, 8, v210
	v_lshl_or_b32 v214, v215, 8, v214
	v_lshl_or_b32 v218, v219, 8, v218
	v_lshl_or_b32 v222, v223, 8, v222
	v_or3_b32 v236, v210, v212, v213
	v_or3_b32 v237, v214, v216, v217
	v_or3_b32 v238, v218, v220, v221
	v_or3_b32 v239, v222, v224, v225
	global_store_dwordx2 v[146:147], v[236:237], off offset:1024 nt
	global_store_dwordx2 v[146:147], v[238:239], off offset:1152 nt
	s_waitcnt vmcnt(13)
	v_mul_f32_e32 v130, 0xbfb8aa3b, v208
	v_fma_f32 v210, v28, v130, v186
	v_fma_f32 v211, v29, v130, v187
	v_fma_f32 v212, v30, v130, v188
	v_fma_f32 v213, v31, v130, v189
	v_fma_f32 v214, v24, v130, v190
	v_fma_f32 v215, v25, v130, v191
	v_fma_f32 v216, v26, v130, v192
	v_fma_f32 v217, v27, v130, v193
	v_fma_f32 v218, v20, v130, v194
	v_fma_f32 v219, v21, v130, v195
	v_fma_f32 v220, v22, v130, v196
	v_fma_f32 v221, v23, v130, v197
	v_fma_f32 v222, v16, v130, v198
	v_fma_f32 v223, v17, v130, v199
	v_fma_f32 v224, v18, v130, v200
	v_fma_f32 v225, v19, v130, v201
	v_exp_f32_e32 v210, v210
	v_exp_f32_e32 v211, v211
	v_exp_f32_e32 v212, v212
	v_exp_f32_e32 v213, v213
	v_exp_f32_e32 v214, v214
	v_exp_f32_e32 v215, v215
	v_exp_f32_e32 v216, v216
	v_exp_f32_e32 v217, v217
	v_exp_f32_e32 v218, v218
	v_exp_f32_e32 v219, v219
	v_exp_f32_e32 v220, v220
	v_exp_f32_e32 v221, v221
	v_exp_f32_e32 v222, v222
	v_exp_f32_e32 v223, v223
	v_exp_f32_e32 v224, v224
	v_exp_f32_e32 v225, v225
	v_add_f32_e32 v210, 1.0, v210
	v_add_f32_e32 v211, 1.0, v211
	v_add_f32_e32 v212, 1.0, v212
	v_add_f32_e32 v213, 1.0, v213
	v_add_f32_e32 v214, 1.0, v214
	v_add_f32_e32 v215, 1.0, v215
	v_add_f32_e32 v216, 1.0, v216
	v_add_f32_e32 v217, 1.0, v217
	v_add_f32_e32 v218, 1.0, v218
	v_add_f32_e32 v219, 1.0, v219
	v_add_f32_e32 v220, 1.0, v220
	v_add_f32_e32 v221, 1.0, v221
	v_add_f32_e32 v222, 1.0, v222
	v_add_f32_e32 v223, 1.0, v223
	v_add_f32_e32 v224, 1.0, v224
	v_add_f32_e32 v225, 1.0, v225
	v_rcp_f32_e32 v210, v210
	v_rcp_f32_e32 v211, v211
	v_rcp_f32_e32 v212, v212
	v_rcp_f32_e32 v213, v213
	v_rcp_f32_e32 v214, v214
	v_rcp_f32_e32 v215, v215
	v_rcp_f32_e32 v216, v216
	v_rcp_f32_e32 v217, v217
	v_rcp_f32_e32 v218, v218
	v_rcp_f32_e32 v219, v219
	v_rcp_f32_e32 v220, v220
	v_rcp_f32_e32 v221, v221
	v_rcp_f32_e32 v222, v222
	v_rcp_f32_e32 v223, v223
	v_rcp_f32_e32 v224, v224
	v_rcp_f32_e32 v225, v225
	v_fma_f32 v210, v210, s84, 0.5
	v_fma_f32 v211, v211, s84, 0.5
	v_fma_f32 v212, v212, s84, 0.5
	v_fma_f32 v213, v213, s84, 0.5
	v_fma_f32 v214, v214, s84, 0.5
	v_fma_f32 v215, v215, s84, 0.5
	v_fma_f32 v216, v216, s84, 0.5
	v_fma_f32 v217, v217, s84, 0.5
	v_fma_f32 v218, v218, s84, 0.5
	v_fma_f32 v219, v219, s84, 0.5
	v_fma_f32 v220, v220, s84, 0.5
	v_fma_f32 v221, v221, s84, 0.5
	v_fma_f32 v222, v222, s84, 0.5
	v_fma_f32 v223, v223, s84, 0.5
	v_fma_f32 v224, v224, s84, 0.5
	v_fma_f32 v225, v225, s84, 0.5
	v_med3_f32 v210, v210, 1.0, v182
	v_med3_f32 v211, v211, 1.0, v182
	v_med3_f32 v212, v212, 1.0, v182
	v_med3_f32 v213, v213, 1.0, v182
	v_med3_f32 v214, v214, 1.0, v182
	v_med3_f32 v215, v215, 1.0, v182
	v_med3_f32 v216, v216, 1.0, v182
	v_med3_f32 v217, v217, 1.0, v182
	v_med3_f32 v218, v218, 1.0, v182
	v_med3_f32 v219, v219, 1.0, v182
	v_med3_f32 v220, v220, 1.0, v182
	v_med3_f32 v221, v221, 1.0, v182
	v_med3_f32 v222, v222, 1.0, v182
	v_med3_f32 v223, v223, 1.0, v182
	v_med3_f32 v224, v224, 1.0, v182
	v_med3_f32 v225, v225, 1.0, v182
	v_cvt_u32_f32_e32 v210, v210
	v_cvt_u32_f32_e32 v211, v211
	v_cvt_u32_f32_sdwa v212, v212 dst_sel:WORD_1 dst_unused:UNUSED_PAD src0_sel:DWORD
	v_cvt_u32_f32_sdwa v213, v213 dst_sel:BYTE_3 dst_unused:UNUSED_PAD src0_sel:DWORD
	v_cvt_u32_f32_e32 v214, v214
	v_cvt_u32_f32_e32 v215, v215
	v_cvt_u32_f32_sdwa v216, v216 dst_sel:WORD_1 dst_unused:UNUSED_PAD src0_sel:DWORD
	v_cvt_u32_f32_sdwa v217, v217 dst_sel:BYTE_3 dst_unused:UNUSED_PAD src0_sel:DWORD
	v_cvt_u32_f32_e32 v218, v218
	v_cvt_u32_f32_e32 v219, v219
	v_cvt_u32_f32_sdwa v220, v220 dst_sel:WORD_1 dst_unused:UNUSED_PAD src0_sel:DWORD
	v_cvt_u32_f32_sdwa v221, v221 dst_sel:BYTE_3 dst_unused:UNUSED_PAD src0_sel:DWORD
	v_cvt_u32_f32_e32 v222, v222
	v_cvt_u32_f32_e32 v223, v223
	v_cvt_u32_f32_sdwa v224, v224 dst_sel:WORD_1 dst_unused:UNUSED_PAD src0_sel:DWORD
	v_cvt_u32_f32_sdwa v225, v225 dst_sel:BYTE_3 dst_unused:UNUSED_PAD src0_sel:DWORD
	v_lshl_or_b32 v210, v211, 8, v210
	v_lshl_or_b32 v214, v215, 8, v214
	v_lshl_or_b32 v218, v219, 8, v218
	v_lshl_or_b32 v222, v223, 8, v222
	v_or3_b32 v236, v210, v212, v213
	v_or3_b32 v237, v214, v216, v217
	v_or3_b32 v238, v218, v220, v221
	v_or3_b32 v239, v222, v224, v225
	global_store_dwordx2 v[146:147], v[236:237], off offset:2048 nt
	global_store_dwordx2 v[146:147], v[238:239], off offset:2176 nt
	s_waitcnt vmcnt(14)
	v_mul_f32_e32 v130, 0xbfb8aa3b, v209
	v_fma_f32 v210, v12, v130, v186
	v_fma_f32 v211, v13, v130, v187
	v_fma_f32 v212, v14, v130, v188
	v_fma_f32 v213, v15, v130, v189
	v_fma_f32 v214, v8, v130, v190
	v_fma_f32 v215, v9, v130, v191
	v_fma_f32 v216, v10, v130, v192
	v_fma_f32 v217, v11, v130, v193
	v_fma_f32 v218, v4, v130, v194
	v_fma_f32 v219, v5, v130, v195
	v_fma_f32 v220, v6, v130, v196
	v_fma_f32 v221, v7, v130, v197
	v_fma_f32 v222, v0, v130, v198
	v_fma_f32 v223, v1, v130, v199
	v_fma_f32 v224, v2, v130, v200
	v_fma_f32 v225, v3, v130, v201
	v_exp_f32_e32 v210, v210
	v_exp_f32_e32 v211, v211
	v_exp_f32_e32 v212, v212
	v_exp_f32_e32 v213, v213
	v_exp_f32_e32 v214, v214
	v_exp_f32_e32 v215, v215
	v_exp_f32_e32 v216, v216
	v_exp_f32_e32 v217, v217
	v_exp_f32_e32 v218, v218
	v_exp_f32_e32 v219, v219
	v_exp_f32_e32 v220, v220
	v_exp_f32_e32 v221, v221
	v_exp_f32_e32 v222, v222
	v_exp_f32_e32 v223, v223
	v_exp_f32_e32 v224, v224
	v_exp_f32_e32 v225, v225
	v_add_f32_e32 v210, 1.0, v210
	v_add_f32_e32 v211, 1.0, v211
	v_add_f32_e32 v212, 1.0, v212
	v_add_f32_e32 v213, 1.0, v213
	v_add_f32_e32 v214, 1.0, v214
	v_add_f32_e32 v215, 1.0, v215
	v_add_f32_e32 v216, 1.0, v216
	v_add_f32_e32 v217, 1.0, v217
	v_add_f32_e32 v218, 1.0, v218
	v_add_f32_e32 v219, 1.0, v219
	v_add_f32_e32 v220, 1.0, v220
	v_add_f32_e32 v221, 1.0, v221
	v_add_f32_e32 v222, 1.0, v222
	v_add_f32_e32 v223, 1.0, v223
	v_add_f32_e32 v224, 1.0, v224
	v_add_f32_e32 v225, 1.0, v225
	v_rcp_f32_e32 v210, v210
	v_rcp_f32_e32 v211, v211
	v_rcp_f32_e32 v212, v212
	v_rcp_f32_e32 v213, v213
	v_rcp_f32_e32 v214, v214
	v_rcp_f32_e32 v215, v215
	v_rcp_f32_e32 v216, v216
	v_rcp_f32_e32 v217, v217
	v_rcp_f32_e32 v218, v218
	v_rcp_f32_e32 v219, v219
	v_rcp_f32_e32 v220, v220
	v_rcp_f32_e32 v221, v221
	v_rcp_f32_e32 v222, v222
	v_rcp_f32_e32 v223, v223
	v_rcp_f32_e32 v224, v224
	v_rcp_f32_e32 v225, v225
	v_fma_f32 v210, v210, s84, 0.5
	v_fma_f32 v211, v211, s84, 0.5
	v_fma_f32 v212, v212, s84, 0.5
	v_fma_f32 v213, v213, s84, 0.5
	v_fma_f32 v214, v214, s84, 0.5
	v_fma_f32 v215, v215, s84, 0.5
	v_fma_f32 v216, v216, s84, 0.5
	v_fma_f32 v217, v217, s84, 0.5
	v_fma_f32 v218, v218, s84, 0.5
	v_fma_f32 v219, v219, s84, 0.5
	v_fma_f32 v220, v220, s84, 0.5
	v_fma_f32 v221, v221, s84, 0.5
	v_fma_f32 v222, v222, s84, 0.5
	v_fma_f32 v223, v223, s84, 0.5
	v_fma_f32 v224, v224, s84, 0.5
	v_fma_f32 v225, v225, s84, 0.5
	v_med3_f32 v210, v210, 1.0, v182
	v_med3_f32 v211, v211, 1.0, v182
	v_med3_f32 v212, v212, 1.0, v182
	v_med3_f32 v213, v213, 1.0, v182
	v_med3_f32 v214, v214, 1.0, v182
	v_med3_f32 v215, v215, 1.0, v182
	v_med3_f32 v216, v216, 1.0, v182
	v_med3_f32 v217, v217, 1.0, v182
	v_med3_f32 v218, v218, 1.0, v182
	v_med3_f32 v219, v219, 1.0, v182
	v_med3_f32 v220, v220, 1.0, v182
	v_med3_f32 v221, v221, 1.0, v182
	v_med3_f32 v222, v222, 1.0, v182
	v_med3_f32 v223, v223, 1.0, v182
	v_med3_f32 v224, v224, 1.0, v182
	v_med3_f32 v225, v225, 1.0, v182
	v_cvt_u32_f32_e32 v210, v210
	v_cvt_u32_f32_e32 v211, v211
	v_cvt_u32_f32_sdwa v212, v212 dst_sel:WORD_1 dst_unused:UNUSED_PAD src0_sel:DWORD
	v_cvt_u32_f32_sdwa v213, v213 dst_sel:BYTE_3 dst_unused:UNUSED_PAD src0_sel:DWORD
	v_cvt_u32_f32_e32 v214, v214
	v_cvt_u32_f32_e32 v215, v215
	v_cvt_u32_f32_sdwa v216, v216 dst_sel:WORD_1 dst_unused:UNUSED_PAD src0_sel:DWORD
	v_cvt_u32_f32_sdwa v217, v217 dst_sel:BYTE_3 dst_unused:UNUSED_PAD src0_sel:DWORD
	v_cvt_u32_f32_e32 v218, v218
	v_cvt_u32_f32_e32 v219, v219
	v_cvt_u32_f32_sdwa v220, v220 dst_sel:WORD_1 dst_unused:UNUSED_PAD src0_sel:DWORD
	v_cvt_u32_f32_sdwa v221, v221 dst_sel:BYTE_3 dst_unused:UNUSED_PAD src0_sel:DWORD
	v_cvt_u32_f32_e32 v222, v222
	v_cvt_u32_f32_e32 v223, v223
	v_cvt_u32_f32_sdwa v224, v224 dst_sel:WORD_1 dst_unused:UNUSED_PAD src0_sel:DWORD
	v_cvt_u32_f32_sdwa v225, v225 dst_sel:BYTE_3 dst_unused:UNUSED_PAD src0_sel:DWORD
	v_lshl_or_b32 v210, v211, 8, v210
	v_lshl_or_b32 v214, v215, 8, v214
	v_lshl_or_b32 v218, v219, 8, v218
	v_lshl_or_b32 v222, v223, 8, v222
	v_or3_b32 v236, v210, v212, v213
	v_or3_b32 v237, v214, v216, v217
	v_or3_b32 v238, v218, v220, v221
	v_or3_b32 v239, v222, v224, v225
	global_store_dwordx2 v[146:147], v[236:237], off offset:3072 nt
	global_store_dwordx2 v[146:147], v[238:239], off offset:3200 nt
	s_mov_b32 s12, 0x40000

.Lhk4_a:
	s_lshl_b32 s50, s31, 11
	s_lshl_b32 s51, s86, 8
	s_add_i32 s50, s50, s51
	s_lshl_b32 s51, s66, 9
	s_add_i32 s50, s50, s51
	s_lshl_b32 s51, s67, 8
	s_add_i32 s50, s50, s51
	v_and_b32_e32 v234, 63, v165
	v_lshl_add_u32 v234, v234, 3, s50
	v_add_u32_e32 v235, 0x1000, v234
	v_add_u32_e32 v236, 0x40000, v234
	v_add_u32_e32 v237, 0x41000, v234
	global_load_dwordx2 v[136:137], v234, s[0:1]
	global_load_dwordx2 v[138:139], v234, s[0:1] offset:512
	global_load_dwordx2 v[140:141], v236, s[0:1]
	global_load_dwordx2 v[142:143], v236, s[0:1] offset:512
	global_load_dwordx2 v[154:155], v234, s[0:1] offset:1024
	global_load_dwordx2 v[156:157], v234, s[0:1] offset:1536
	global_load_dwordx2 v[158:159], v236, s[0:1] offset:1024
	global_load_dwordx2 v[160:161], v236, s[0:1] offset:1536
	global_load_dwordx2 v[170:171], v234, s[0:1] offset:2048
	global_load_dwordx2 v[172:173], v234, s[0:1] offset:2560
	global_load_dwordx2 v[174:175], v236, s[0:1] offset:2048
	global_load_dwordx2 v[176:177], v236, s[0:1] offset:2560
	global_load_dwordx2 v[178:179], v234, s[0:1] offset:3072
	global_load_dwordx2 v[180:181], v234, s[0:1] offset:3584
	global_load_dwordx2 v[182:183], v236, s[0:1] offset:3072
	global_load_dwordx2 v[184:185], v236, s[0:1] offset:3584
	global_load_dwordx2 v[186:187], v235, s[0:1]
	global_load_dwordx2 v[188:189], v235, s[0:1] offset:512
	global_load_dwordx2 v[190:191], v237, s[0:1]
	global_load_dwordx2 v[192:193], v237, s[0:1] offset:512
	global_load_dwordx2 v[194:195], v235, s[0:1] offset:1024
	global_load_dwordx2 v[196:197], v235, s[0:1] offset:1536
	global_load_dwordx2 v[198:199], v237, s[0:1] offset:1024
	global_load_dwordx2 v[200:201], v237, s[0:1] offset:1536
	global_load_dwordx2 v[202:203], v235, s[0:1] offset:2048
	global_load_dwordx2 v[204:205], v235, s[0:1] offset:2560
	global_load_dwordx2 v[206:207], v237, s[0:1] offset:2048
	global_load_dwordx2 v[208:209], v237, s[0:1] offset:2560
	global_load_dwordx2 v[210:211], v235, s[0:1] offset:3072
	global_load_dwordx2 v[212:213], v235, s[0:1] offset:3584
	global_load_dwordx2 v[214:215], v237, s[0:1] offset:3072
	global_load_dwordx2 v[216:217], v237, s[0:1] offset:3584
	s_waitcnt vmcnt(28)
	v_cvt_f32_ubyte0_e32 v218, v136
	v_cvt_f32_ubyte1_e32 v219, v136
	v_cvt_f32_ubyte2_e32 v220, v136
	v_cvt_f32_ubyte3_e32 v221, v136
	v_cvt_f32_ubyte0_e32 v222, v137
	v_cvt_f32_ubyte1_e32 v223, v137
	v_cvt_f32_ubyte2_e32 v224, v137
	v_cvt_f32_ubyte3_e32 v225, v137
	v_cvt_f32_ubyte0_e32 v226, v140
	v_cvt_f32_ubyte1_e32 v227, v140
	v_cvt_f32_ubyte2_e32 v228, v140
	v_cvt_f32_ubyte3_e32 v229, v140
	v_cvt_f32_ubyte0_e32 v230, v141
	v_cvt_f32_ubyte1_e32 v231, v141
	v_cvt_f32_ubyte2_e32 v232, v141
	v_cvt_f32_ubyte3_e32 v233, v141
	v_rcp_iflag_f32_e32 v226, v226
	v_rcp_iflag_f32_e32 v227, v227
	v_rcp_iflag_f32_e32 v228, v228
	v_rcp_iflag_f32_e32 v229, v229
	v_rcp_iflag_f32_e32 v230, v230
	v_rcp_iflag_f32_e32 v231, v231
	v_rcp_iflag_f32_e32 v232, v232
	v_rcp_iflag_f32_e32 v233, v233
	v_pk_mul_f32 v[218:219], v[218:219], v[226:227]
	v_pk_mul_f32 v[220:221], v[220:221], v[228:229]
	v_pk_mul_f32 v[222:223], v[222:223], v[230:231]
	v_pk_mul_f32 v[224:225], v[224:225], v[232:233]
	v_pk_mul_f32 v[128:129], v[128:129], v[218:219]
	v_pk_mul_f32 v[130:131], v[130:131], v[220:221]
	v_pk_mul_f32 v[124:125], v[124:125], v[222:223]
	v_pk_mul_f32 v[126:127], v[126:127], v[224:225]
	v_cvt_f32_ubyte0_e32 v218, v138
	v_cvt_f32_ubyte1_e32 v219, v138
	v_cvt_f32_ubyte2_e32 v220, v138
	v_cvt_f32_ubyte3_e32 v221, v138
	v_cvt_f32_ubyte0_e32 v222, v139
	v_cvt_f32_ubyte1_e32 v223, v139
	v_cvt_f32_ubyte2_e32 v224, v139
	v_cvt_f32_ubyte3_e32 v225, v139
	v_cvt_f32_ubyte0_e32 v226, v142
	v_cvt_f32_ubyte1_e32 v227, v142
	v_cvt_f32_ubyte2_e32 v228, v142
	v_cvt_f32_ubyte3_e32 v229, v142
	v_cvt_f32_ubyte0_e32 v230, v143
	v_cvt_f32_ubyte1_e32 v231, v143
	v_cvt_f32_ubyte2_e32 v232, v143
	v_cvt_f32_ubyte3_e32 v233, v143
	v_rcp_iflag_f32_e32 v226, v226
	v_rcp_iflag_f32_e32 v227, v227
	v_rcp_iflag_f32_e32 v228, v228
	v_rcp_iflag_f32_e32 v229, v229
	v_rcp_iflag_f32_e32 v230, v230
	v_rcp_iflag_f32_e32 v231, v231
	v_rcp_iflag_f32_e32 v232, v232
	v_rcp_iflag_f32_e32 v233, v233
	v_pk_mul_f32 v[218:219], v[218:219], v[226:227]
	v_pk_mul_f32 v[220:221], v[220:221], v[228:229]
	v_pk_mul_f32 v[222:223], v[222:223], v[230:231]
	v_pk_mul_f32 v[224:225], v[224:225], v[232:233]
	v_pk_mul_f32 v[120:121], v[120:121], v[218:219]
	v_pk_mul_f32 v[122:123], v[122:123], v[220:221]
	v_pk_mul_f32 v[116:117], v[116:117], v[222:223]
	v_pk_mul_f32 v[118:119], v[118:119], v[224:225]
	s_waitcnt vmcnt(24)
	v_cvt_f32_ubyte0_e32 v218, v154
	v_cvt_f32_ubyte1_e32 v219, v154
	v_cvt_f32_ubyte2_e32 v220, v154
	v_cvt_f32_ubyte3_e32 v221, v154
	v_cvt_f32_ubyte0_e32 v222, v155
	v_cvt_f32_ubyte1_e32 v223, v155
	v_cvt_f32_ubyte2_e32 v224, v155
	v_cvt_f32_ubyte3_e32 v225, v155
	v_cvt_f32_ubyte0_e32 v226, v158
	v_cvt_f32_ubyte1_e32 v227, v158
	v_cvt_f32_ubyte2_e32 v228, v158
	v_cvt_f32_ubyte3_e32 v229, v158
	v_cvt_f32_ubyte0_e32 v230, v159
	v_cvt_f32_ubyte1_e32 v231, v159
	v_cvt_f32_ubyte2_e32 v232, v159
	v_cvt_f32_ubyte3_e32 v233, v159
	v_rcp_iflag_f32_e32 v226, v226
	v_rcp_iflag_f32_e32 v227, v227
	v_rcp_iflag_f32_e32 v228, v228
	v_rcp_iflag_f32_e32 v229, v229
	v_rcp_iflag_f32_e32 v230, v230
	v_rcp_iflag_f32_e32 v231, v231
	v_rcp_iflag_f32_e32 v232, v232
	v_rcp_iflag_f32_e32 v233, v233
	v_pk_mul_f32 v[218:219], v[218:219], v[226:227]
	v_pk_mul_f32 v[220:221], v[220:221], v[228:229]
	v_pk_mul_f32 v[222:223], v[222:223], v[230:231]
	v_pk_mul_f32 v[224:225], v[224:225], v[232:233]
	v_pk_mul_f32 v[112:113], v[112:113], v[218:219]
	v_pk_mul_f32 v[114:115], v[114:115], v[220:221]
	v_pk_mul_f32 v[108:109], v[108:109], v[222:223]
	v_pk_mul_f32 v[110:111], v[110:111], v[224:225]
	v_cvt_f32_ubyte0_e32 v218, v156
	v_cvt_f32_ubyte1_e32 v219, v156
	v_cvt_f32_ubyte2_e32 v220, v156
	v_cvt_f32_ubyte3_e32 v221, v156
	v_cvt_f32_ubyte0_e32 v222, v157
	v_cvt_f32_ubyte1_e32 v223, v157
	v_cvt_f32_ubyte2_e32 v224, v157
	v_cvt_f32_ubyte3_e32 v225, v157
	v_cvt_f32_ubyte0_e32 v226, v160
	v_cvt_f32_ubyte1_e32 v227, v160
	v_cvt_f32_ubyte2_e32 v228, v160
	v_cvt_f32_ubyte3_e32 v229, v160
	v_cvt_f32_ubyte0_e32 v230, v161
	v_cvt_f32_ubyte1_e32 v231, v161
	v_cvt_f32_ubyte2_e32 v232, v161
	v_cvt_f32_ubyte3_e32 v233, v161
	v_rcp_iflag_f32_e32 v226, v226
	v_rcp_iflag_f32_e32 v227, v227
	v_rcp_iflag_f32_e32 v228, v228
	v_rcp_iflag_f32_e32 v229, v229
	v_rcp_iflag_f32_e32 v230, v230
	v_rcp_iflag_f32_e32 v231, v231
	v_rcp_iflag_f32_e32 v232, v232
	v_rcp_iflag_f32_e32 v233, v233
	v_pk_mul_f32 v[218:219], v[218:219], v[226:227]
	v_pk_mul_f32 v[220:221], v[220:221], v[228:229]
	v_pk_mul_f32 v[222:223], v[222:223], v[230:231]
	v_pk_mul_f32 v[224:225], v[224:225], v[232:233]
	v_pk_mul_f32 v[104:105], v[104:105], v[218:219]
	v_pk_mul_f32 v[106:107], v[106:107], v[220:221]
	v_pk_mul_f32 v[100:101], v[100:101], v[222:223]
	v_pk_mul_f32 v[102:103], v[102:103], v[224:225]
	s_waitcnt vmcnt(20)
	v_cvt_f32_ubyte0_e32 v218, v170
	v_cvt_f32_ubyte1_e32 v219, v170
	v_cvt_f32_ubyte2_e32 v220, v170
	v_cvt_f32_ubyte3_e32 v221, v170
	v_cvt_f32_ubyte0_e32 v222, v171
	v_cvt_f32_ubyte1_e32 v223, v171
	v_cvt_f32_ubyte2_e32 v224, v171
	v_cvt_f32_ubyte3_e32 v225, v171
	v_cvt_f32_ubyte0_e32 v226, v174
	v_cvt_f32_ubyte1_e32 v227, v174
	v_cvt_f32_ubyte2_e32 v228, v174
	v_cvt_f32_ubyte3_e32 v229, v174
	v_cvt_f32_ubyte0_e32 v230, v175
	v_cvt_f32_ubyte1_e32 v231, v175
	v_cvt_f32_ubyte2_e32 v232, v175
	v_cvt_f32_ubyte3_e32 v233, v175
	v_rcp_iflag_f32_e32 v226, v226
	v_rcp_iflag_f32_e32 v227, v227
	v_rcp_iflag_f32_e32 v228, v228
	v_rcp_iflag_f32_e32 v229, v229
	v_rcp_iflag_f32_e32 v230, v230
	v_rcp_iflag_f32_e32 v231, v231
	v_rcp_iflag_f32_e32 v232, v232
	v_rcp_iflag_f32_e32 v233, v233
	v_pk_mul_f32 v[218:219], v[218:219], v[226:227]
	v_pk_mul_f32 v[220:221], v[220:221], v[228:229]
	v_pk_mul_f32 v[222:223], v[222:223], v[230:231]
	v_pk_mul_f32 v[224:225], v[224:225], v[232:233]
	v_pk_mul_f32 v[96:97], v[96:97], v[218:219]
	v_pk_mul_f32 v[98:99], v[98:99], v[220:221]
	v_pk_mul_f32 v[92:93], v[92:93], v[222:223]
	v_pk_mul_f32 v[94:95], v[94:95], v[224:225]
	v_cvt_f32_ubyte0_e32 v218, v172
	v_cvt_f32_ubyte1_e32 v219, v172
	v_cvt_f32_ubyte2_e32 v220, v172
	v_cvt_f32_ubyte3_e32 v221, v172
	v_cvt_f32_ubyte0_e32 v222, v173
	v_cvt_f32_ubyte1_e32 v223, v173
	v_cvt_f32_ubyte2_e32 v224, v173
	v_cvt_f32_ubyte3_e32 v225, v173
	v_cvt_f32_ubyte0_e32 v226, v176
	v_cvt_f32_ubyte1_e32 v227, v176
	v_cvt_f32_ubyte2_e32 v228, v176
	v_cvt_f32_ubyte3_e32 v229, v176
	v_cvt_f32_ubyte0_e32 v230, v177
	v_cvt_f32_ubyte1_e32 v231, v177
	v_cvt_f32_ubyte2_e32 v232, v177
	v_cvt_f32_ubyte3_e32 v233, v177
	v_rcp_iflag_f32_e32 v226, v226
	v_rcp_iflag_f32_e32 v227, v227
	v_rcp_iflag_f32_e32 v228, v228
	v_rcp_iflag_f32_e32 v229, v229
	v_rcp_iflag_f32_e32 v230, v230
	v_rcp_iflag_f32_e32 v231, v231
	v_rcp_iflag_f32_e32 v232, v232
	v_rcp_iflag_f32_e32 v233, v233
	v_pk_mul_f32 v[218:219], v[218:219], v[226:227]
	v_pk_mul_f32 v[220:221], v[220:221], v[228:229]
	v_pk_mul_f32 v[222:223], v[222:223], v[230:231]
	v_pk_mul_f32 v[224:225], v[224:225], v[232:233]
	v_pk_mul_f32 v[88:89], v[88:89], v[218:219]
	v_pk_mul_f32 v[90:91], v[90:91], v[220:221]
	v_pk_mul_f32 v[84:85], v[84:85], v[222:223]
	v_pk_mul_f32 v[86:87], v[86:87], v[224:225]
	s_waitcnt vmcnt(16)
	v_cvt_f32_ubyte0_e32 v218, v178
	v_cvt_f32_ubyte1_e32 v219, v178
	v_cvt_f32_ubyte2_e32 v220, v178
	v_cvt_f32_ubyte3_e32 v221, v178
	v_cvt_f32_ubyte0_e32 v222, v179
	v_cvt_f32_ubyte1_e32 v223, v179
	v_cvt_f32_ubyte2_e32 v224, v179
	v_cvt_f32_ubyte3_e32 v225, v179
	v_cvt_f32_ubyte0_e32 v226, v182
	v_cvt_f32_ubyte1_e32 v227, v182
	v_cvt_f32_ubyte2_e32 v228, v182
	v_cvt_f32_ubyte3_e32 v229, v182
	v_cvt_f32_ubyte0_e32 v230, v183
	v_cvt_f32_ubyte1_e32 v231, v183
	v_cvt_f32_ubyte2_e32 v232, v183
	v_cvt_f32_ubyte3_e32 v233, v183
	v_rcp_iflag_f32_e32 v226, v226
	v_rcp_iflag_f32_e32 v227, v227
	v_rcp_iflag_f32_e32 v228, v228
	v_rcp_iflag_f32_e32 v229, v229
	v_rcp_iflag_f32_e32 v230, v230
	v_rcp_iflag_f32_e32 v231, v231
	v_rcp_iflag_f32_e32 v232, v232
	v_rcp_iflag_f32_e32 v233, v233
	v_pk_mul_f32 v[218:219], v[218:219], v[226:227]
	v_pk_mul_f32 v[220:221], v[220:221], v[228:229]
	v_pk_mul_f32 v[222:223], v[222:223], v[230:231]
	v_pk_mul_f32 v[224:225], v[224:225], v[232:233]
	v_pk_mul_f32 v[80:81], v[80:81], v[218:219]
	v_pk_mul_f32 v[82:83], v[82:83], v[220:221]
	v_pk_mul_f32 v[76:77], v[76:77], v[222:223]
	v_pk_mul_f32 v[78:79], v[78:79], v[224:225]
	v_cvt_f32_ubyte0_e32 v218, v180
	v_cvt_f32_ubyte1_e32 v219, v180
	v_cvt_f32_ubyte2_e32 v220, v180
	v_cvt_f32_ubyte3_e32 v221, v180
	v_cvt_f32_ubyte0_e32 v222, v181
	v_cvt_f32_ubyte1_e32 v223, v181
	v_cvt_f32_ubyte2_e32 v224, v181
	v_cvt_f32_ubyte3_e32 v225, v181
	v_cvt_f32_ubyte0_e32 v226, v184
	v_cvt_f32_ubyte1_e32 v227, v184
	v_cvt_f32_ubyte2_e32 v228, v184
	v_cvt_f32_ubyte3_e32 v229, v184
	v_cvt_f32_ubyte0_e32 v230, v185
	v_cvt_f32_ubyte1_e32 v231, v185
	v_cvt_f32_ubyte2_e32 v232, v185
	v_cvt_f32_ubyte3_e32 v233, v185
	v_rcp_iflag_f32_e32 v226, v226
	v_rcp_iflag_f32_e32 v227, v227
	v_rcp_iflag_f32_e32 v228, v228
	v_rcp_iflag_f32_e32 v229, v229
	v_rcp_iflag_f32_e32 v230, v230
	v_rcp_iflag_f32_e32 v231, v231
	v_rcp_iflag_f32_e32 v232, v232
	v_rcp_iflag_f32_e32 v233, v233
	v_pk_mul_f32 v[218:219], v[218:219], v[226:227]
	v_pk_mul_f32 v[220:221], v[220:221], v[228:229]
	v_pk_mul_f32 v[222:223], v[222:223], v[230:231]
	v_pk_mul_f32 v[224:225], v[224:225], v[232:233]
	v_pk_mul_f32 v[72:73], v[72:73], v[218:219]
	v_pk_mul_f32 v[74:75], v[74:75], v[220:221]
	v_pk_mul_f32 v[68:69], v[68:69], v[222:223]
	v_pk_mul_f32 v[70:71], v[70:71], v[224:225]
	s_waitcnt vmcnt(12)
	v_cvt_f32_ubyte0_e32 v218, v186
	v_cvt_f32_ubyte1_e32 v219, v186
	v_cvt_f32_ubyte2_e32 v220, v186
	v_cvt_f32_ubyte3_e32 v221, v186
	v_cvt_f32_ubyte0_e32 v222, v187
	v_cvt_f32_ubyte1_e32 v223, v187
	v_cvt_f32_ubyte2_e32 v224, v187
	v_cvt_f32_ubyte3_e32 v225, v187
	v_cvt_f32_ubyte0_e32 v226, v190
	v_cvt_f32_ubyte1_e32 v227, v190
	v_cvt_f32_ubyte2_e32 v228, v190
	v_cvt_f32_ubyte3_e32 v229, v190
	v_cvt_f32_ubyte0_e32 v230, v191
	v_cvt_f32_ubyte1_e32 v231, v191
	v_cvt_f32_ubyte2_e32 v232, v191
	v_cvt_f32_ubyte3_e32 v233, v191
	v_rcp_iflag_f32_e32 v226, v226
	v_rcp_iflag_f32_e32 v227, v227
	v_rcp_iflag_f32_e32 v228, v228
	v_rcp_iflag_f32_e32 v229, v229
	v_rcp_iflag_f32_e32 v230, v230
	v_rcp_iflag_f32_e32 v231, v231
	v_rcp_iflag_f32_e32 v232, v232
	v_rcp_iflag_f32_e32 v233, v233
	v_pk_mul_f32 v[218:219], v[218:219], v[226:227]
	v_pk_mul_f32 v[220:221], v[220:221], v[228:229]
	v_pk_mul_f32 v[222:223], v[222:223], v[230:231]
	v_pk_mul_f32 v[224:225], v[224:225], v[232:233]
	v_pk_mul_f32 v[64:65], v[64:65], v[218:219]
	v_pk_mul_f32 v[66:67], v[66:67], v[220:221]
	v_pk_mul_f32 v[60:61], v[60:61], v[222:223]
	v_pk_mul_f32 v[62:63], v[62:63], v[224:225]
	v_cvt_f32_ubyte0_e32 v218, v188
	v_cvt_f32_ubyte1_e32 v219, v188
	v_cvt_f32_ubyte2_e32 v220, v188
	v_cvt_f32_ubyte3_e32 v221, v188
	v_cvt_f32_ubyte0_e32 v222, v189
	v_cvt_f32_ubyte1_e32 v223, v189
	v_cvt_f32_ubyte2_e32 v224, v189
	v_cvt_f32_ubyte3_e32 v225, v189
	v_cvt_f32_ubyte0_e32 v226, v192
	v_cvt_f32_ubyte1_e32 v227, v192
	v_cvt_f32_ubyte2_e32 v228, v192
	v_cvt_f32_ubyte3_e32 v229, v192
	v_cvt_f32_ubyte0_e32 v230, v193
	v_cvt_f32_ubyte1_e32 v231, v193
	v_cvt_f32_ubyte2_e32 v232, v193
	v_cvt_f32_ubyte3_e32 v233, v193
	v_rcp_iflag_f32_e32 v226, v226
	v_rcp_iflag_f32_e32 v227, v227
	v_rcp_iflag_f32_e32 v228, v228
	v_rcp_iflag_f32_e32 v229, v229
	v_rcp_iflag_f32_e32 v230, v230
	v_rcp_iflag_f32_e32 v231, v231
	v_rcp_iflag_f32_e32 v232, v232
	v_rcp_iflag_f32_e32 v233, v233
	v_pk_mul_f32 v[218:219], v[218:219], v[226:227]
	v_pk_mul_f32 v[220:221], v[220:221], v[228:229]
	v_pk_mul_f32 v[222:223], v[222:223], v[230:231]
	v_pk_mul_f32 v[224:225], v[224:225], v[232:233]
	v_pk_mul_f32 v[56:57], v[56:57], v[218:219]
	v_pk_mul_f32 v[58:59], v[58:59], v[220:221]
	v_pk_mul_f32 v[52:53], v[52:53], v[222:223]
	v_pk_mul_f32 v[54:55], v[54:55], v[224:225]
	s_waitcnt vmcnt(8)
	v_cvt_f32_ubyte0_e32 v218, v194
	v_cvt_f32_ubyte1_e32 v219, v194
	v_cvt_f32_ubyte2_e32 v220, v194
	v_cvt_f32_ubyte3_e32 v221, v194
	v_cvt_f32_ubyte0_e32 v222, v195
	v_cvt_f32_ubyte1_e32 v223, v195
	v_cvt_f32_ubyte2_e32 v224, v195
	v_cvt_f32_ubyte3_e32 v225, v195
	v_cvt_f32_ubyte0_e32 v226, v198
	v_cvt_f32_ubyte1_e32 v227, v198
	v_cvt_f32_ubyte2_e32 v228, v198
	v_cvt_f32_ubyte3_e32 v229, v198
	v_cvt_f32_ubyte0_e32 v230, v199
	v_cvt_f32_ubyte1_e32 v231, v199
	v_cvt_f32_ubyte2_e32 v232, v199
	v_cvt_f32_ubyte3_e32 v233, v199
	v_rcp_iflag_f32_e32 v226, v226
	v_rcp_iflag_f32_e32 v227, v227
	v_rcp_iflag_f32_e32 v228, v228
	v_rcp_iflag_f32_e32 v229, v229
	v_rcp_iflag_f32_e32 v230, v230
	v_rcp_iflag_f32_e32 v231, v231
	v_rcp_iflag_f32_e32 v232, v232
	v_rcp_iflag_f32_e32 v233, v233
	v_pk_mul_f32 v[218:219], v[218:219], v[226:227]
	v_pk_mul_f32 v[220:221], v[220:221], v[228:229]
	v_pk_mul_f32 v[222:223], v[222:223], v[230:231]
	v_pk_mul_f32 v[224:225], v[224:225], v[232:233]
	v_pk_mul_f32 v[48:49], v[48:49], v[218:219]
	v_pk_mul_f32 v[50:51], v[50:51], v[220:221]
	v_pk_mul_f32 v[44:45], v[44:45], v[222:223]
	v_pk_mul_f32 v[46:47], v[46:47], v[224:225]
	v_cvt_f32_ubyte0_e32 v218, v196
	v_cvt_f32_ubyte1_e32 v219, v196
	v_cvt_f32_ubyte2_e32 v220, v196
	v_cvt_f32_ubyte3_e32 v221, v196
	v_cvt_f32_ubyte0_e32 v222, v197
	v_cvt_f32_ubyte1_e32 v223, v197
	v_cvt_f32_ubyte2_e32 v224, v197
	v_cvt_f32_ubyte3_e32 v225, v197
	v_cvt_f32_ubyte0_e32 v226, v200
	v_cvt_f32_ubyte1_e32 v227, v200
	v_cvt_f32_ubyte2_e32 v228, v200
	v_cvt_f32_ubyte3_e32 v229, v200
	v_cvt_f32_ubyte0_e32 v230, v201
	v_cvt_f32_ubyte1_e32 v231, v201
	v_cvt_f32_ubyte2_e32 v232, v201
	v_cvt_f32_ubyte3_e32 v233, v201
	v_rcp_iflag_f32_e32 v226, v226
	v_rcp_iflag_f32_e32 v227, v227
	v_rcp_iflag_f32_e32 v228, v228
	v_rcp_iflag_f32_e32 v229, v229
	v_rcp_iflag_f32_e32 v230, v230
	v_rcp_iflag_f32_e32 v231, v231
	v_rcp_iflag_f32_e32 v232, v232
	v_rcp_iflag_f32_e32 v233, v233
	v_pk_mul_f32 v[218:219], v[218:219], v[226:227]
	v_pk_mul_f32 v[220:221], v[220:221], v[228:229]
	v_pk_mul_f32 v[222:223], v[222:223], v[230:231]
	v_pk_mul_f32 v[224:225], v[224:225], v[232:233]
	v_pk_mul_f32 v[40:41], v[40:41], v[218:219]
	v_pk_mul_f32 v[42:43], v[42:43], v[220:221]
	v_pk_mul_f32 v[36:37], v[36:37], v[222:223]
	v_pk_mul_f32 v[38:39], v[38:39], v[224:225]
	s_waitcnt vmcnt(4)
	v_cvt_f32_ubyte0_e32 v218, v202
	v_cvt_f32_ubyte1_e32 v219, v202
	v_cvt_f32_ubyte2_e32 v220, v202
	v_cvt_f32_ubyte3_e32 v221, v202
	v_cvt_f32_ubyte0_e32 v222, v203
	v_cvt_f32_ubyte1_e32 v223, v203
	v_cvt_f32_ubyte2_e32 v224, v203
	v_cvt_f32_ubyte3_e32 v225, v203
	v_cvt_f32_ubyte0_e32 v226, v206
	v_cvt_f32_ubyte1_e32 v227, v206
	v_cvt_f32_ubyte2_e32 v228, v206
	v_cvt_f32_ubyte3_e32 v229, v206
	v_cvt_f32_ubyte0_e32 v230, v207
	v_cvt_f32_ubyte1_e32 v231, v207
	v_cvt_f32_ubyte2_e32 v232, v207
	v_cvt_f32_ubyte3_e32 v233, v207
	v_rcp_iflag_f32_e32 v226, v226
	v_rcp_iflag_f32_e32 v227, v227
	v_rcp_iflag_f32_e32 v228, v228
	v_rcp_iflag_f32_e32 v229, v229
	v_rcp_iflag_f32_e32 v230, v230
	v_rcp_iflag_f32_e32 v231, v231
	v_rcp_iflag_f32_e32 v232, v232
	v_rcp_iflag_f32_e32 v233, v233
	v_pk_mul_f32 v[218:219], v[218:219], v[226:227]
	v_pk_mul_f32 v[220:221], v[220:221], v[228:229]
	v_pk_mul_f32 v[222:223], v[222:223], v[230:231]
	v_pk_mul_f32 v[224:225], v[224:225], v[232:233]
	v_pk_mul_f32 v[32:33], v[32:33], v[218:219]
	v_pk_mul_f32 v[34:35], v[34:35], v[220:221]
	v_pk_mul_f32 v[28:29], v[28:29], v[222:223]
	v_pk_mul_f32 v[30:31], v[30:31], v[224:225]
	v_cvt_f32_ubyte0_e32 v218, v204
	v_cvt_f32_ubyte1_e32 v219, v204
	v_cvt_f32_ubyte2_e32 v220, v204
	v_cvt_f32_ubyte3_e32 v221, v204
	v_cvt_f32_ubyte0_e32 v222, v205
	v_cvt_f32_ubyte1_e32 v223, v205
	v_cvt_f32_ubyte2_e32 v224, v205
	v_cvt_f32_ubyte3_e32 v225, v205
	v_cvt_f32_ubyte0_e32 v226, v208
	v_cvt_f32_ubyte1_e32 v227, v208
	v_cvt_f32_ubyte2_e32 v228, v208
	v_cvt_f32_ubyte3_e32 v229, v208
	v_cvt_f32_ubyte0_e32 v230, v209
	v_cvt_f32_ubyte1_e32 v231, v209
	v_cvt_f32_ubyte2_e32 v232, v209
	v_cvt_f32_ubyte3_e32 v233, v209
	v_rcp_iflag_f32_e32 v226, v226
	v_rcp_iflag_f32_e32 v227, v227
	v_rcp_iflag_f32_e32 v228, v228
	v_rcp_iflag_f32_e32 v229, v229
	v_rcp_iflag_f32_e32 v230, v230
	v_rcp_iflag_f32_e32 v231, v231
	v_rcp_iflag_f32_e32 v232, v232
	v_rcp_iflag_f32_e32 v233, v233
	v_pk_mul_f32 v[218:219], v[218:219], v[226:227]
	v_pk_mul_f32 v[220:221], v[220:221], v[228:229]
	v_pk_mul_f32 v[222:223], v[222:223], v[230:231]
	v_pk_mul_f32 v[224:225], v[224:225], v[232:233]
	v_pk_mul_f32 v[24:25], v[24:25], v[218:219]
	v_pk_mul_f32 v[26:27], v[26:27], v[220:221]
	v_pk_mul_f32 v[20:21], v[20:21], v[222:223]
	v_pk_mul_f32 v[22:23], v[22:23], v[224:225]
	s_waitcnt vmcnt(0)
	v_cvt_f32_ubyte0_e32 v218, v210
	v_cvt_f32_ubyte1_e32 v219, v210
	v_cvt_f32_ubyte2_e32 v220, v210
	v_cvt_f32_ubyte3_e32 v221, v210
	v_cvt_f32_ubyte0_e32 v222, v211
	v_cvt_f32_ubyte1_e32 v223, v211
	v_cvt_f32_ubyte2_e32 v224, v211
	v_cvt_f32_ubyte3_e32 v225, v211
	v_cvt_f32_ubyte0_e32 v226, v214
	v_cvt_f32_ubyte1_e32 v227, v214
	v_cvt_f32_ubyte2_e32 v228, v214
	v_cvt_f32_ubyte3_e32 v229, v214
	v_cvt_f32_ubyte0_e32 v230, v215
	v_cvt_f32_ubyte1_e32 v231, v215
	v_cvt_f32_ubyte2_e32 v232, v215
	v_cvt_f32_ubyte3_e32 v233, v215
	v_rcp_iflag_f32_e32 v226, v226
	v_rcp_iflag_f32_e32 v227, v227
	v_rcp_iflag_f32_e32 v228, v228
	v_rcp_iflag_f32_e32 v229, v229
	v_rcp_iflag_f32_e32 v230, v230
	v_rcp_iflag_f32_e32 v231, v231
	v_rcp_iflag_f32_e32 v232, v232
	v_rcp_iflag_f32_e32 v233, v233
	v_pk_mul_f32 v[218:219], v[218:219], v[226:227]
	v_pk_mul_f32 v[220:221], v[220:221], v[228:229]
	v_pk_mul_f32 v[222:223], v[222:223], v[230:231]
	v_pk_mul_f32 v[224:225], v[224:225], v[232:233]
	v_pk_mul_f32 v[16:17], v[16:17], v[218:219]
	v_pk_mul_f32 v[18:19], v[18:19], v[220:221]
	v_pk_mul_f32 v[12:13], v[12:13], v[222:223]
	v_pk_mul_f32 v[14:15], v[14:15], v[224:225]
	v_cvt_f32_ubyte0_e32 v218, v212
	v_cvt_f32_ubyte1_e32 v219, v212
	v_cvt_f32_ubyte2_e32 v220, v212
	v_cvt_f32_ubyte3_e32 v221, v212
	v_cvt_f32_ubyte0_e32 v222, v213
	v_cvt_f32_ubyte1_e32 v223, v213
	v_cvt_f32_ubyte2_e32 v224, v213
	v_cvt_f32_ubyte3_e32 v225, v213
	v_cvt_f32_ubyte0_e32 v226, v216
	v_cvt_f32_ubyte1_e32 v227, v216
	v_cvt_f32_ubyte2_e32 v228, v216
	v_cvt_f32_ubyte3_e32 v229, v216
	v_cvt_f32_ubyte0_e32 v230, v217
	v_cvt_f32_ubyte1_e32 v231, v217
	v_cvt_f32_ubyte2_e32 v232, v217
	v_cvt_f32_ubyte3_e32 v233, v217
	v_rcp_iflag_f32_e32 v226, v226
	v_rcp_iflag_f32_e32 v227, v227
	v_rcp_iflag_f32_e32 v228, v228
	v_rcp_iflag_f32_e32 v229, v229
	v_rcp_iflag_f32_e32 v230, v230
	v_rcp_iflag_f32_e32 v231, v231
	v_rcp_iflag_f32_e32 v232, v232
	v_rcp_iflag_f32_e32 v233, v233
	v_pk_mul_f32 v[218:219], v[218:219], v[226:227]
	v_pk_mul_f32 v[220:221], v[220:221], v[228:229]
	v_pk_mul_f32 v[222:223], v[222:223], v[230:231]
	v_pk_mul_f32 v[224:225], v[224:225], v[232:233]
	v_pk_mul_f32 v[8:9], v[8:9], v[218:219]
	v_pk_mul_f32 v[10:11], v[10:11], v[220:221]
	v_pk_mul_f32 v[4:5], v[4:5], v[222:223]
	v_pk_mul_f32 v[6:7], v[6:7], v[224:225]
	s_cmp_eq_u64 s[18:19], 0
	s_cbranch_scc0 .Lhk4_b
	s_barrier

.LBB0_494:
	v_add_u32_e32 v220, s31, v150
	v_or_b32_e32 v219, s86, v151
	s_lshl_b32 s50, s31, 11
	s_lshl_b32 s51, s86, 8
	s_add_i32 s50, s50, s51
	s_lshl_b32 s51, s66, 9
	s_add_i32 s50, s50, s51
	s_lshl_b32 s51, s67, 8
	s_add_i32 s50, s50, s51
	s_add_i32 s50, s50, 0x40000
	v_and_b32_e32 v218, 63, v165
	v_lshl_add_u32 v218, v218, 3, s50
	v_add_u32_e32 v221, 0x1000, v218
	v_lshlrev_b32_e32 v219, 1, v219
	v_lshl_add_u32 v219, v220, 11, v219
	global_load_dwordx2 v[170:171], v218, s[0:1]
	global_load_dwordx2 v[172:173], v218, s[0:1] offset:512
	global_load_dwordx2 v[174:175], v218, s[0:1] offset:1024
	global_load_dwordx2 v[176:177], v218, s[0:1] offset:1536
	global_load_dwordx2 v[178:179], v218, s[0:1] offset:2048
	global_load_dwordx2 v[180:181], v218, s[0:1] offset:2560
	s_waitcnt vmcnt(4)
	v_cvt_f32_ubyte0_e32 v202, v170
	v_cvt_f32_ubyte1_e32 v203, v170
	v_cvt_f32_ubyte2_e32 v204, v170
	v_cvt_f32_ubyte3_e32 v205, v170
	v_cvt_f32_ubyte0_e32 v206, v171
	v_cvt_f32_ubyte1_e32 v207, v171
	v_cvt_f32_ubyte2_e32 v208, v171
	v_cvt_f32_ubyte3_e32 v209, v171
	v_cvt_f32_ubyte0_e32 v210, v172
	v_cvt_f32_ubyte1_e32 v211, v172
	v_cvt_f32_ubyte2_e32 v212, v172
	v_cvt_f32_ubyte3_e32 v213, v172
	v_cvt_f32_ubyte0_e32 v214, v173
	v_cvt_f32_ubyte1_e32 v215, v173
	v_cvt_f32_ubyte2_e32 v216, v173
	v_cvt_f32_ubyte3_e32 v217, v173
	v_pk_mul_f32 v[202:203], v[202:203], s[28:29] op_sel_hi:[1,0]
	v_pk_mul_f32 v[204:205], v[204:205], s[28:29] op_sel_hi:[1,0]
	v_pk_mul_f32 v[206:207], v[206:207], s[28:29] op_sel_hi:[1,0]
	v_pk_mul_f32 v[208:209], v[208:209], s[28:29] op_sel_hi:[1,0]
	v_pk_mul_f32 v[210:211], v[210:211], s[28:29] op_sel_hi:[1,0]
	v_pk_mul_f32 v[212:213], v[212:213], s[28:29] op_sel_hi:[1,0]
	v_pk_mul_f32 v[214:215], v[214:215], s[28:29] op_sel_hi:[1,0]
	v_pk_mul_f32 v[216:217], v[216:217], s[28:29] op_sel_hi:[1,0]
	v_pk_mul_f32 v[128:129], v[128:129], v[202:203]
	v_pk_mul_f32 v[130:131], v[130:131], v[204:205]
	v_pk_mul_f32 v[124:125], v[124:125], v[206:207]
	v_pk_mul_f32 v[126:127], v[126:127], v[208:209]
	v_pk_mul_f32 v[120:121], v[120:121], v[210:211]
	v_pk_mul_f32 v[122:123], v[122:123], v[212:213]
	v_pk_mul_f32 v[116:117], v[116:117], v[214:215]
	v_pk_mul_f32 v[118:119], v[118:119], v[216:217]
	v_cvt_pk_bf16_f32 v128, v128, v129
	v_cvt_pk_bf16_f32 v129, v130, v131
	v_cvt_pk_bf16_f32 v130, v124, v125
	v_cvt_pk_bf16_f32 v131, v126, v127
	v_cvt_pk_bf16_f32 v120, v120, v121
	v_cvt_pk_bf16_f32 v121, v122, v123
	v_cvt_pk_bf16_f32 v122, v116, v117
	v_cvt_pk_bf16_f32 v123, v118, v119
	global_store_dwordx4 v219, v[128:131], s[48:49]
	global_store_dwordx4 v219, v[120:123], s[48:49] offset:256
	global_load_dwordx2 v[182:183], v218, s[0:1] offset:3072
	global_load_dwordx2 v[184:185], v218, s[0:1] offset:3584
	s_waitcnt vmcnt(6)
	v_cvt_f32_ubyte0_e32 v202, v174
	v_cvt_f32_ubyte1_e32 v203, v174
	v_cvt_f32_ubyte2_e32 v204, v174
	v_cvt_f32_ubyte3_e32 v205, v174
	v_cvt_f32_ubyte0_e32 v206, v175
	v_cvt_f32_ubyte1_e32 v207, v175
	v_cvt_f32_ubyte2_e32 v208, v175
	v_cvt_f32_ubyte3_e32 v209, v175
	v_cvt_f32_ubyte0_e32 v210, v176
	v_cvt_f32_ubyte1_e32 v211, v176
	v_cvt_f32_ubyte2_e32 v212, v176
	v_cvt_f32_ubyte3_e32 v213, v176
	v_cvt_f32_ubyte0_e32 v214, v177
	v_cvt_f32_ubyte1_e32 v215, v177
	v_cvt_f32_ubyte2_e32 v216, v177
	v_cvt_f32_ubyte3_e32 v217, v177
	v_pk_mul_f32 v[202:203], v[202:203], s[28:29] op_sel_hi:[1,0]
	v_pk_mul_f32 v[204:205], v[204:205], s[28:29] op_sel_hi:[1,0]
	v_pk_mul_f32 v[206:207], v[206:207], s[28:29] op_sel_hi:[1,0]
	v_pk_mul_f32 v[208:209], v[208:209], s[28:29] op_sel_hi:[1,0]
	v_pk_mul_f32 v[210:211], v[210:211], s[28:29] op_sel_hi:[1,0]
	v_pk_mul_f32 v[212:213], v[212:213], s[28:29] op_sel_hi:[1,0]
	v_pk_mul_f32 v[214:215], v[214:215], s[28:29] op_sel_hi:[1,0]
	v_pk_mul_f32 v[216:217], v[216:217], s[28:29] op_sel_hi:[1,0]
	v_pk_mul_f32 v[112:113], v[112:113], v[202:203]
	v_pk_mul_f32 v[114:115], v[114:115], v[204:205]
	v_pk_mul_f32 v[108:109], v[108:109], v[206:207]
	v_pk_mul_f32 v[110:111], v[110:111], v[208:209]
	v_pk_mul_f32 v[104:105], v[104:105], v[210:211]
	v_pk_mul_f32 v[106:107], v[106:107], v[212:213]
	v_pk_mul_f32 v[100:101], v[100:101], v[214:215]
	v_pk_mul_f32 v[102:103], v[102:103], v[216:217]
	v_cvt_pk_bf16_f32 v112, v112, v113
	v_cvt_pk_bf16_f32 v113, v114, v115
	v_cvt_pk_bf16_f32 v114, v108, v109
	v_cvt_pk_bf16_f32 v115, v110, v111
	v_cvt_pk_bf16_f32 v104, v104, v105
	v_cvt_pk_bf16_f32 v105, v106, v107
	v_cvt_pk_bf16_f32 v106, v100, v101
	v_cvt_pk_bf16_f32 v107, v102, v103
	v_add_u32_e32 v220, 0x8000, v219
	global_store_dwordx4 v220, v[112:115], s[48:49]
	global_store_dwordx4 v220, v[104:107], s[48:49] offset:256
	global_load_dwordx2 v[170:171], v221, s[0:1]
	global_load_dwordx2 v[172:173], v221, s[0:1] offset:512
	s_waitcnt vmcnt(8)
	v_cvt_f32_ubyte0_e32 v202, v178
	v_cvt_f32_ubyte1_e32 v203, v178
	v_cvt_f32_ubyte2_e32 v204, v178
	v_cvt_f32_ubyte3_e32 v205, v178
	v_cvt_f32_ubyte0_e32 v206, v179
	v_cvt_f32_ubyte1_e32 v207, v179
	v_cvt_f32_ubyte2_e32 v208, v179
	v_cvt_f32_ubyte3_e32 v209, v179
	v_cvt_f32_ubyte0_e32 v210, v180
	v_cvt_f32_ubyte1_e32 v211, v180
	v_cvt_f32_ubyte2_e32 v212, v180
	v_cvt_f32_ubyte3_e32 v213, v180
	v_cvt_f32_ubyte0_e32 v214, v181
	v_cvt_f32_ubyte1_e32 v215, v181
	v_cvt_f32_ubyte2_e32 v216, v181
	v_cvt_f32_ubyte3_e32 v217, v181
	v_pk_mul_f32 v[202:203], v[202:203], s[28:29] op_sel_hi:[1,0]
	v_pk_mul_f32 v[204:205], v[204:205], s[28:29] op_sel_hi:[1,0]
	v_pk_mul_f32 v[206:207], v[206:207], s[28:29] op_sel_hi:[1,0]
	v_pk_mul_f32 v[208:209], v[208:209], s[28:29] op_sel_hi:[1,0]
	v_pk_mul_f32 v[210:211], v[210:211], s[28:29] op_sel_hi:[1,0]
	v_pk_mul_f32 v[212:213], v[212:213], s[28:29] op_sel_hi:[1,0]
	v_pk_mul_f32 v[214:215], v[214:215], s[28:29] op_sel_hi:[1,0]
	v_pk_mul_f32 v[216:217], v[216:217], s[28:29] op_sel_hi:[1,0]
	v_pk_mul_f32 v[96:97], v[96:97], v[202:203]
	v_pk_mul_f32 v[98:99], v[98:99], v[204:205]
	v_pk_mul_f32 v[92:93], v[92:93], v[206:207]
	v_pk_mul_f32 v[94:95], v[94:95], v[208:209]
	v_pk_mul_f32 v[88:89], v[88:89], v[210:211]
	v_pk_mul_f32 v[90:91], v[90:91], v[212:213]
	v_pk_mul_f32 v[84:85], v[84:85], v[214:215]
	v_pk_mul_f32 v[86:87], v[86:87], v[216:217]
	v_cvt_pk_bf16_f32 v96, v96, v97
	v_cvt_pk_bf16_f32 v97, v98, v99
	v_cvt_pk_bf16_f32 v98, v92, v93
	v_cvt_pk_bf16_f32 v99, v94, v95
	v_cvt_pk_bf16_f32 v88, v88, v89
	v_cvt_pk_bf16_f32 v89, v90, v91
	v_cvt_pk_bf16_f32 v90, v84, v85
	v_cvt_pk_bf16_f32 v91, v86, v87
	v_add_u32_e32 v220, 0x10000, v219
	global_store_dwordx4 v220, v[96:99], s[48:49]
	global_store_dwordx4 v220, v[88:91], s[48:49] offset:256
	global_load_dwordx2 v[174:175], v221, s[0:1] offset:1024
	global_load_dwordx2 v[176:177], v221, s[0:1] offset:1536
	s_waitcnt vmcnt(8)
	v_cvt_f32_ubyte0_e32 v202, v182
	v_cvt_f32_ubyte1_e32 v203, v182
	v_cvt_f32_ubyte2_e32 v204, v182
	v_cvt_f32_ubyte3_e32 v205, v182
	v_cvt_f32_ubyte0_e32 v206, v183
	v_cvt_f32_ubyte1_e32 v207, v183
	v_cvt_f32_ubyte2_e32 v208, v183
	v_cvt_f32_ubyte3_e32 v209, v183
	v_cvt_f32_ubyte0_e32 v210, v184
	v_cvt_f32_ubyte1_e32 v211, v184
	v_cvt_f32_ubyte2_e32 v212, v184
	v_cvt_f32_ubyte3_e32 v213, v184
	v_cvt_f32_ubyte0_e32 v214, v185
	v_cvt_f32_ubyte1_e32 v215, v185
	v_cvt_f32_ubyte2_e32 v216, v185
	v_cvt_f32_ubyte3_e32 v217, v185
	v_pk_mul_f32 v[202:203], v[202:203], s[28:29] op_sel_hi:[1,0]
	v_pk_mul_f32 v[204:205], v[204:205], s[28:29] op_sel_hi:[1,0]
	v_pk_mul_f32 v[206:207], v[206:207], s[28:29] op_sel_hi:[1,0]
	v_pk_mul_f32 v[208:209], v[208:209], s[28:29] op_sel_hi:[1,0]
	v_pk_mul_f32 v[210:211], v[210:211], s[28:29] op_sel_hi:[1,0]
	v_pk_mul_f32 v[212:213], v[212:213], s[28:29] op_sel_hi:[1,0]
	v_pk_mul_f32 v[214:215], v[214:215], s[28:29] op_sel_hi:[1,0]
	v_pk_mul_f32 v[216:217], v[216:217], s[28:29] op_sel_hi:[1,0]
	v_pk_mul_f32 v[80:81], v[80:81], v[202:203]
	v_pk_mul_f32 v[82:83], v[82:83], v[204:205]
	v_pk_mul_f32 v[76:77], v[76:77], v[206:207]
	v_pk_mul_f32 v[78:79], v[78:79], v[208:209]
	v_pk_mul_f32 v[72:73], v[72:73], v[210:211]
	v_pk_mul_f32 v[74:75], v[74:75], v[212:213]
	v_pk_mul_f32 v[68:69], v[68:69], v[214:215]
	v_pk_mul_f32 v[70:71], v[70:71], v[216:217]
	v_cvt_pk_bf16_f32 v80, v80, v81
	v_cvt_pk_bf16_f32 v81, v82, v83
	v_cvt_pk_bf16_f32 v82, v76, v77
	v_cvt_pk_bf16_f32 v83, v78, v79
	v_cvt_pk_bf16_f32 v72, v72, v73
	v_cvt_pk_bf16_f32 v73, v74, v75
	v_cvt_pk_bf16_f32 v74, v68, v69
	v_cvt_pk_bf16_f32 v75, v70, v71
	v_add_u32_e32 v220, 0x18000, v219
	global_store_dwordx4 v220, v[80:83], s[48:49]
	global_store_dwordx4 v220, v[72:75], s[48:49] offset:256
	global_load_dwordx2 v[178:179], v221, s[0:1] offset:2048
	global_load_dwordx2 v[180:181], v221, s[0:1] offset:2560
	s_waitcnt vmcnt(8)
	v_cvt_f32_ubyte0_e32 v202, v170
	v_cvt_f32_ubyte1_e32 v203, v170
	v_cvt_f32_ubyte2_e32 v204, v170
	v_cvt_f32_ubyte3_e32 v205, v170
	v_cvt_f32_ubyte0_e32 v206, v171
	v_cvt_f32_ubyte1_e32 v207, v171
	v_cvt_f32_ubyte2_e32 v208, v171
	v_cvt_f32_ubyte3_e32 v209, v171
	v_cvt_f32_ubyte0_e32 v210, v172
	v_cvt_f32_ubyte1_e32 v211, v172
	v_cvt_f32_ubyte2_e32 v212, v172
	v_cvt_f32_ubyte3_e32 v213, v172
	v_cvt_f32_ubyte0_e32 v214, v173
	v_cvt_f32_ubyte1_e32 v215, v173
	v_cvt_f32_ubyte2_e32 v216, v173
	v_cvt_f32_ubyte3_e32 v217, v173
	v_pk_mul_f32 v[202:203], v[202:203], s[28:29] op_sel_hi:[1,0]
	v_pk_mul_f32 v[204:205], v[204:205], s[28:29] op_sel_hi:[1,0]
	v_pk_mul_f32 v[206:207], v[206:207], s[28:29] op_sel_hi:[1,0]
	v_pk_mul_f32 v[208:209], v[208:209], s[28:29] op_sel_hi:[1,0]
	v_pk_mul_f32 v[210:211], v[210:211], s[28:29] op_sel_hi:[1,0]
	v_pk_mul_f32 v[212:213], v[212:213], s[28:29] op_sel_hi:[1,0]
	v_pk_mul_f32 v[214:215], v[214:215], s[28:29] op_sel_hi:[1,0]
	v_pk_mul_f32 v[216:217], v[216:217], s[28:29] op_sel_hi:[1,0]
	v_pk_mul_f32 v[64:65], v[64:65], v[202:203]
	v_pk_mul_f32 v[66:67], v[66:67], v[204:205]
	v_pk_mul_f32 v[60:61], v[60:61], v[206:207]
	v_pk_mul_f32 v[62:63], v[62:63], v[208:209]
	v_pk_mul_f32 v[56:57], v[56:57], v[210:211]
	v_pk_mul_f32 v[58:59], v[58:59], v[212:213]
	v_pk_mul_f32 v[52:53], v[52:53], v[214:215]
	v_pk_mul_f32 v[54:55], v[54:55], v[216:217]
	v_cvt_pk_bf16_f32 v64, v64, v65
	v_cvt_pk_bf16_f32 v65, v66, v67
	v_cvt_pk_bf16_f32 v66, v60, v61
	v_cvt_pk_bf16_f32 v67, v62, v63
	v_cvt_pk_bf16_f32 v56, v56, v57
	v_cvt_pk_bf16_f32 v57, v58, v59
	v_cvt_pk_bf16_f32 v58, v52, v53
	v_cvt_pk_bf16_f32 v59, v54, v55
	v_add_u32_e32 v220, 0x40000, v219
	global_store_dwordx4 v220, v[64:67], s[48:49]
	global_store_dwordx4 v220, v[56:59], s[48:49] offset:256
	global_load_dwordx2 v[182:183], v221, s[0:1] offset:3072
	global_load_dwordx2 v[184:185], v221, s[0:1] offset:3584
	s_waitcnt vmcnt(8)
	v_cvt_f32_ubyte0_e32 v202, v174
	v_cvt_f32_ubyte1_e32 v203, v174
	v_cvt_f32_ubyte2_e32 v204, v174
	v_cvt_f32_ubyte3_e32 v205, v174
	v_cvt_f32_ubyte0_e32 v206, v175
	v_cvt_f32_ubyte1_e32 v207, v175
	v_cvt_f32_ubyte2_e32 v208, v175
	v_cvt_f32_ubyte3_e32 v209, v175
	v_cvt_f32_ubyte0_e32 v210, v176
	v_cvt_f32_ubyte1_e32 v211, v176
	v_cvt_f32_ubyte2_e32 v212, v176
	v_cvt_f32_ubyte3_e32 v213, v176
	v_cvt_f32_ubyte0_e32 v214, v177
	v_cvt_f32_ubyte1_e32 v215, v177
	v_cvt_f32_ubyte2_e32 v216, v177
	v_cvt_f32_ubyte3_e32 v217, v177
	v_pk_mul_f32 v[202:203], v[202:203], s[28:29] op_sel_hi:[1,0]
	v_pk_mul_f32 v[204:205], v[204:205], s[28:29] op_sel_hi:[1,0]
	v_pk_mul_f32 v[206:207], v[206:207], s[28:29] op_sel_hi:[1,0]
	v_pk_mul_f32 v[208:209], v[208:209], s[28:29] op_sel_hi:[1,0]
	v_pk_mul_f32 v[210:211], v[210:211], s[28:29] op_sel_hi:[1,0]
	v_pk_mul_f32 v[212:213], v[212:213], s[28:29] op_sel_hi:[1,0]
	v_pk_mul_f32 v[214:215], v[214:215], s[28:29] op_sel_hi:[1,0]
	v_pk_mul_f32 v[216:217], v[216:217], s[28:29] op_sel_hi:[1,0]
	v_pk_mul_f32 v[48:49], v[48:49], v[202:203]
	v_pk_mul_f32 v[50:51], v[50:51], v[204:205]
	v_pk_mul_f32 v[44:45], v[44:45], v[206:207]
	v_pk_mul_f32 v[46:47], v[46:47], v[208:209]
	v_pk_mul_f32 v[40:41], v[40:41], v[210:211]
	v_pk_mul_f32 v[42:43], v[42:43], v[212:213]
	v_pk_mul_f32 v[36:37], v[36:37], v[214:215]
	v_pk_mul_f32 v[38:39], v[38:39], v[216:217]
	v_cvt_pk_bf16_f32 v48, v48, v49
	v_cvt_pk_bf16_f32 v49, v50, v51
	v_cvt_pk_bf16_f32 v50, v44, v45
	v_cvt_pk_bf16_f32 v51, v46, v47
	v_cvt_pk_bf16_f32 v40, v40, v41
	v_cvt_pk_bf16_f32 v41, v42, v43
	v_cvt_pk_bf16_f32 v42, v36, v37
	v_cvt_pk_bf16_f32 v43, v38, v39
	v_add_u32_e32 v220, 0x48000, v219
	global_store_dwordx4 v220, v[48:51], s[48:49]
	global_store_dwordx4 v220, v[40:43], s[48:49] offset:256
	s_waitcnt vmcnt(6)
	v_cvt_f32_ubyte0_e32 v202, v178
	v_cvt_f32_ubyte1_e32 v203, v178
	v_cvt_f32_ubyte2_e32 v204, v178
	v_cvt_f32_ubyte3_e32 v205, v178
	v_cvt_f32_ubyte0_e32 v206, v179
	v_cvt_f32_ubyte1_e32 v207, v179
	v_cvt_f32_ubyte2_e32 v208, v179
	v_cvt_f32_ubyte3_e32 v209, v179
	v_cvt_f32_ubyte0_e32 v210, v180
	v_cvt_f32_ubyte1_e32 v211, v180
	v_cvt_f32_ubyte2_e32 v212, v180
	v_cvt_f32_ubyte3_e32 v213, v180
	v_cvt_f32_ubyte0_e32 v214, v181
	v_cvt_f32_ubyte1_e32 v215, v181
	v_cvt_f32_ubyte2_e32 v216, v181
	v_cvt_f32_ubyte3_e32 v217, v181
	v_pk_mul_f32 v[202:203], v[202:203], s[28:29] op_sel_hi:[1,0]
	v_pk_mul_f32 v[204:205], v[204:205], s[28:29] op_sel_hi:[1,0]
	v_pk_mul_f32 v[206:207], v[206:207], s[28:29] op_sel_hi:[1,0]
	v_pk_mul_f32 v[208:209], v[208:209], s[28:29] op_sel_hi:[1,0]
	v_pk_mul_f32 v[210:211], v[210:211], s[28:29] op_sel_hi:[1,0]
	v_pk_mul_f32 v[212:213], v[212:213], s[28:29] op_sel_hi:[1,0]
	v_pk_mul_f32 v[214:215], v[214:215], s[28:29] op_sel_hi:[1,0]
	v_pk_mul_f32 v[216:217], v[216:217], s[28:29] op_sel_hi:[1,0]
	v_pk_mul_f32 v[32:33], v[32:33], v[202:203]
	v_pk_mul_f32 v[34:35], v[34:35], v[204:205]
	v_pk_mul_f32 v[28:29], v[28:29], v[206:207]
	v_pk_mul_f32 v[30:31], v[30:31], v[208:209]
	v_pk_mul_f32 v[24:25], v[24:25], v[210:211]
	v_pk_mul_f32 v[26:27], v[26:27], v[212:213]
	v_pk_mul_f32 v[20:21], v[20:21], v[214:215]
	v_pk_mul_f32 v[22:23], v[22:23], v[216:217]
	v_cvt_pk_bf16_f32 v32, v32, v33
	v_cvt_pk_bf16_f32 v33, v34, v35
	v_cvt_pk_bf16_f32 v34, v28, v29
	v_cvt_pk_bf16_f32 v35, v30, v31
	v_cvt_pk_bf16_f32 v24, v24, v25
	v_cvt_pk_bf16_f32 v25, v26, v27
	v_cvt_pk_bf16_f32 v26, v20, v21
	v_cvt_pk_bf16_f32 v27, v22, v23
	v_add_u32_e32 v220, 0x50000, v219
	global_store_dwordx4 v220, v[32:35], s[48:49]
	global_store_dwordx4 v220, v[24:27], s[48:49] offset:256
	s_waitcnt vmcnt(4)
	v_cvt_f32_ubyte0_e32 v202, v182
	v_cvt_f32_ubyte1_e32 v203, v182
	v_cvt_f32_ubyte2_e32 v204, v182
	v_cvt_f32_ubyte3_e32 v205, v182
	v_cvt_f32_ubyte0_e32 v206, v183
	v_cvt_f32_ubyte1_e32 v207, v183
	v_cvt_f32_ubyte2_e32 v208, v183
	v_cvt_f32_ubyte3_e32 v209, v183
	v_cvt_f32_ubyte0_e32 v210, v184
	v_cvt_f32_ubyte1_e32 v211, v184
	v_cvt_f32_ubyte2_e32 v212, v184
	v_cvt_f32_ubyte3_e32 v213, v184
	v_cvt_f32_ubyte0_e32 v214, v185
	v_cvt_f32_ubyte1_e32 v215, v185
	v_cvt_f32_ubyte2_e32 v216, v185
	v_cvt_f32_ubyte3_e32 v217, v185
	v_pk_mul_f32 v[202:203], v[202:203], s[28:29] op_sel_hi:[1,0]
	v_pk_mul_f32 v[204:205], v[204:205], s[28:29] op_sel_hi:[1,0]
	v_pk_mul_f32 v[206:207], v[206:207], s[28:29] op_sel_hi:[1,0]
	v_pk_mul_f32 v[208:209], v[208:209], s[28:29] op_sel_hi:[1,0]
	v_pk_mul_f32 v[210:211], v[210:211], s[28:29] op_sel_hi:[1,0]
	v_pk_mul_f32 v[212:213], v[212:213], s[28:29] op_sel_hi:[1,0]
	v_pk_mul_f32 v[214:215], v[214:215], s[28:29] op_sel_hi:[1,0]
	v_pk_mul_f32 v[216:217], v[216:217], s[28:29] op_sel_hi:[1,0]
	v_pk_mul_f32 v[16:17], v[16:17], v[202:203]
	v_pk_mul_f32 v[18:19], v[18:19], v[204:205]
	v_pk_mul_f32 v[12:13], v[12:13], v[206:207]
	v_pk_mul_f32 v[14:15], v[14:15], v[208:209]
	v_pk_mul_f32 v[8:9], v[8:9], v[210:211]
	v_pk_mul_f32 v[10:11], v[10:11], v[212:213]
	v_pk_mul_f32 v[4:5], v[4:5], v[214:215]
	v_pk_mul_f32 v[6:7], v[6:7], v[216:217]
	v_cvt_pk_bf16_f32 v16, v16, v17
	v_cvt_pk_bf16_f32 v17, v18, v19
	v_cvt_pk_bf16_f32 v18, v12, v13
	v_cvt_pk_bf16_f32 v19, v14, v15
	v_cvt_pk_bf16_f32 v8, v8, v9
	v_cvt_pk_bf16_f32 v9, v10, v11
	v_cvt_pk_bf16_f32 v10, v4, v5
	v_cvt_pk_bf16_f32 v11, v6, v7
	v_add_u32_e32 v220, 0x58000, v219
	global_store_dwordx4 v220, v[16:19], s[48:49]
	global_store_dwordx4 v220, v[8:11], s[48:49] offset:256
	s_andn2_b64 vcc, exec, s[4:5]
	s_mov_b64 s[4:5], -1
	s_cbranch_vccnz .LBB0_481
	s_andn2_b64 vcc, exec, s[16:17]
	s_cbranch_vccnz .LBB0_480
	s_barrier
	s_branch .LBB0_480
